# GEMM K-loops: LDS-DMA in saddr form and B-fragment ds_read base hoisted (no VALU in load segments)
# speedup vs baseline: 1.0035x; 1.0035x over previous
.LBB0_200:
	s_ashr_i32 s23, s22, 31
	s_lshl_b64 s[6:7], s[22:23], 20
	s_add_u32 s6, s29, s6
	s_addc_u32 s7, s34, s7
	s_ashr_i32 s25, s24, 31
	s_lshl_b64 s[36:37], s[24:25], 1
	s_add_u32 s6, s6, s36
	s_addc_u32 s7, s7, s37
	s_and_b64 s[44:45], s[52:53], exec
	s_cselect_b32 s23, s7, s43
	s_cselect_b32 s25, s6, s42
	s_ashr_i32 s27, s26, 31
	s_lshl_b64 s[44:45], s[26:27], 20
	s_add_u32 s27, s35, s44
	s_addc_u32 s41, s54, s45
	s_add_u32 s36, s27, s36
	s_addc_u32 s37, s41, s37
	s_and_b64 s[44:45], s[52:53], exec
	s_cselect_b32 s27, s37, s51
	s_cselect_b32 s41, s36, s50
	s_add_i32 s44, s33, -2
	s_add_u32 s42, s42, 0x80080
	s_addc_u32 s43, s43, 0
	s_add_u32 s45, s50, 0x100
	v_mov_b32_e32 v2, 0
	s_addc_u32 s58, s51, 0
	s_mov_b32 s50, 0
	v_mov_b32_e32 v3, v2
	v_mov_b32_e32 v4, v2
	v_mov_b32_e32 v5, v2
	v_mov_b32_e32 v6, v2
	v_mov_b32_e32 v7, v2
	v_mov_b32_e32 v8, v2
	v_mov_b32_e32 v9, v2
	v_mov_b32_e32 v14, v2
	v_mov_b32_e32 v15, v2
	v_mov_b32_e32 v16, v2
	v_mov_b32_e32 v17, v2
	v_mov_b32_e32 v22, v2
	v_mov_b32_e32 v23, v2
	v_mov_b32_e32 v24, v2
	v_mov_b32_e32 v25, v2
	v_mov_b32_e32 v30, v2
	v_mov_b32_e32 v31, v2
	v_mov_b32_e32 v32, v2
	v_mov_b32_e32 v33, v2
	v_mov_b32_e32 v38, v2
	v_mov_b32_e32 v39, v2
	v_mov_b32_e32 v40, v2
	v_mov_b32_e32 v41, v2
	v_mov_b32_e32 v46, v2
	v_mov_b32_e32 v47, v2
	v_mov_b32_e32 v48, v2
	v_mov_b32_e32 v49, v2
	v_mov_b32_e32 v54, v2
	v_mov_b32_e32 v55, v2
	v_mov_b32_e32 v56, v2
	v_mov_b32_e32 v57, v2
	v_mov_b32_e32 v10, v2
	v_mov_b32_e32 v11, v2
	v_mov_b32_e32 v12, v2
	v_mov_b32_e32 v13, v2
	v_mov_b32_e32 v18, v2
	v_mov_b32_e32 v19, v2
	v_mov_b32_e32 v20, v2
	v_mov_b32_e32 v21, v2
	v_mov_b32_e32 v26, v2
	v_mov_b32_e32 v27, v2
	v_mov_b32_e32 v28, v2
	v_mov_b32_e32 v29, v2
	v_mov_b32_e32 v34, v2
	v_mov_b32_e32 v35, v2
	v_mov_b32_e32 v36, v2
	v_mov_b32_e32 v37, v2
	v_mov_b32_e32 v42, v2
	v_mov_b32_e32 v43, v2
	v_mov_b32_e32 v44, v2
	v_mov_b32_e32 v45, v2
	v_mov_b32_e32 v50, v2
	v_mov_b32_e32 v51, v2
	v_mov_b32_e32 v52, v2
	v_mov_b32_e32 v53, v2
	v_mov_b32_e32 v58, v2
	v_mov_b32_e32 v59, v2
	v_mov_b32_e32 v60, v2
	v_mov_b32_e32 v61, v2
	v_mov_b32_e32 v62, v2
	v_mov_b32_e32 v63, v2
	v_mov_b32_e32 v64, v2
	v_mov_b32_e32 v65, v2
	v_mov_b32_e32 v66, v2
	v_mov_b32_e32 v67, v2
	v_mov_b32_e32 v68, v2
	v_mov_b32_e32 v69, v2
	v_mov_b32_e32 v70, v2
	v_mov_b32_e32 v71, v2
	v_mov_b32_e32 v72, v2
	v_mov_b32_e32 v73, v2
	v_mov_b32_e32 v78, v2
	v_mov_b32_e32 v79, v2
	v_mov_b32_e32 v80, v2
	v_mov_b32_e32 v81, v2
	v_mov_b32_e32 v86, v2
	v_mov_b32_e32 v87, v2
	v_mov_b32_e32 v88, v2
	v_mov_b32_e32 v89, v2
	v_mov_b32_e32 v94, v2
	v_mov_b32_e32 v95, v2
	v_mov_b32_e32 v96, v2
	v_mov_b32_e32 v97, v2
	v_mov_b32_e32 v102, v2
	v_mov_b32_e32 v103, v2
	v_mov_b32_e32 v104, v2
	v_mov_b32_e32 v105, v2
	v_mov_b32_e32 v110, v2
	v_mov_b32_e32 v111, v2
	v_mov_b32_e32 v112, v2
	v_mov_b32_e32 v113, v2
	v_mov_b32_e32 v118, v2
	v_mov_b32_e32 v119, v2
	v_mov_b32_e32 v120, v2
	v_mov_b32_e32 v121, v2
	v_mov_b32_e32 v74, v2
	v_mov_b32_e32 v75, v2
	v_mov_b32_e32 v76, v2
	v_mov_b32_e32 v77, v2
	v_mov_b32_e32 v82, v2
	v_mov_b32_e32 v83, v2
	v_mov_b32_e32 v84, v2
	v_mov_b32_e32 v85, v2
	v_mov_b32_e32 v90, v2
	v_mov_b32_e32 v91, v2
	v_mov_b32_e32 v92, v2
	v_mov_b32_e32 v93, v2
	v_mov_b32_e32 v98, v2
	v_mov_b32_e32 v99, v2
	v_mov_b32_e32 v100, v2
	v_mov_b32_e32 v101, v2
	v_mov_b32_e32 v106, v2
	v_mov_b32_e32 v107, v2
	v_mov_b32_e32 v108, v2
	v_mov_b32_e32 v109, v2
	v_mov_b32_e32 v114, v2
	v_mov_b32_e32 v115, v2
	v_mov_b32_e32 v116, v2
	v_mov_b32_e32 v117, v2
	v_mov_b32_e32 v122, v2
	v_mov_b32_e32 v123, v2
	v_mov_b32_e32 v124, v2
	v_mov_b32_e32 v125, v2
	v_mov_b32_e32 v126, v2
	v_mov_b32_e32 v127, v2
	v_mov_b32_e32 v128, v2
	v_mov_b32_e32 v129, v2
	v_add_u32_e32 v253, 0x10000, v147
.LBB0_201:
	s_add_i32 s59, s50, 2
	s_add_u32 s51, s42, 0xfff80080
	s_addc_u32 s52, s43, -1
	s_add_i32 s70, 0, 0x10000
	s_cmp_eq_u32 s44, s50
	s_cselect_b32 s53, s23, s52
	s_cselect_b32 s52, s25, s51
	s_cselect_b32 s51, s27, s58
	s_cselect_b32 s50, s41, s45
	s_add_i32 s74, 0, 0x14000
	ds_read_b128 v[150:153], v253
	ds_read_b128 v[154:157], v253 offset:1024
	ds_read_b128 v[158:161], v253 offset:2048
	ds_read_b128 v[162:165], v253 offset:3072
	ds_read_b128 v[166:169], v253 offset:16384
	ds_read_b128 v[170:173], v253 offset:17408
	ds_read_b128 v[174:177], v253 offset:18432
	ds_read_b128 v[178:181], v253 offset:19456
	s_add_i32 m0, s31, 0xc000
	ds_read_b128 v[182:185], v149
	ds_read_b128 v[186:189], v149 offset:1024
	ds_read_b128 v[190:193], v149 offset:2048
	ds_read_b128 v[204:207], v149 offset:3072
	ds_read_b128 v[208:211], v149 offset:4096
	ds_read_b128 v[212:215], v149 offset:5120
	ds_read_b128 v[216:219], v149 offset:6144
	ds_read_b128 v[220:223], v149 offset:7168
	global_load_lds_dwordx4 v140, s[42:43]
	s_add_i32 m0, s31, 0xe000
	s_nop 0
	global_load_lds_dwordx4 v142, s[42:43]
	s_waitcnt vmcnt(8)
	s_waitcnt lgkmcnt(0)
	s_barrier
	s_setprio 1
	s_waitcnt lgkmcnt(0)
	v_mfma_f32_16x16x32_bf16 v[126:129], v[150:153], v[182:185], v[126:129]
	v_mfma_f32_16x16x32_bf16 v[122:125], v[158:161], v[182:185], v[122:125]
	v_mfma_f32_16x16x32_bf16 v[114:117], v[150:153], v[190:193], v[114:117]
	v_mfma_f32_16x16x32_bf16 v[106:109], v[158:161], v[190:193], v[106:109]
	v_mfma_f32_16x16x32_bf16 v[98:101], v[150:153], v[208:211], v[98:101]
	v_mfma_f32_16x16x32_bf16 v[90:93], v[158:161], v[208:211], v[90:93]
	v_mfma_f32_16x16x32_bf16 v[82:85], v[150:153], v[216:219], v[82:85]
	v_mfma_f32_16x16x32_bf16 v[74:77], v[158:161], v[216:219], v[74:77]
	v_mfma_f32_16x16x32_bf16 v[126:129], v[154:157], v[186:189], v[126:129]
	v_mfma_f32_16x16x32_bf16 v[122:125], v[162:165], v[186:189], v[122:125]
	v_mfma_f32_16x16x32_bf16 v[114:117], v[154:157], v[204:207], v[114:117]
	v_mfma_f32_16x16x32_bf16 v[106:109], v[162:165], v[204:207], v[106:109]
	v_mfma_f32_16x16x32_bf16 v[98:101], v[154:157], v[212:215], v[98:101]
	v_mfma_f32_16x16x32_bf16 v[90:93], v[162:165], v[212:215], v[90:93]
	v_mfma_f32_16x16x32_bf16 v[82:85], v[154:157], v[220:223], v[82:85]
	v_mfma_f32_16x16x32_bf16 v[74:77], v[162:165], v[220:223], v[74:77]
	s_setprio 0
	s_setprio 1
	v_mfma_f32_16x16x32_bf16 v[118:121], v[166:169], v[182:185], v[118:121]
	v_mfma_f32_16x16x32_bf16 v[110:113], v[174:177], v[182:185], v[110:113]
	v_mfma_f32_16x16x32_bf16 v[102:105], v[166:169], v[190:193], v[102:105]
	v_mfma_f32_16x16x32_bf16 v[94:97], v[174:177], v[190:193], v[94:97]
	v_mfma_f32_16x16x32_bf16 v[86:89], v[166:169], v[208:211], v[86:89]
	v_mfma_f32_16x16x32_bf16 v[78:81], v[174:177], v[208:211], v[78:81]
	v_mfma_f32_16x16x32_bf16 v[70:73], v[166:169], v[216:219], v[70:73]
	v_mfma_f32_16x16x32_bf16 v[66:69], v[174:177], v[216:219], v[66:69]
	v_mfma_f32_16x16x32_bf16 v[118:121], v[170:173], v[186:189], v[118:121]
	v_mfma_f32_16x16x32_bf16 v[110:113], v[178:181], v[186:189], v[110:113]
	v_mfma_f32_16x16x32_bf16 v[102:105], v[170:173], v[204:207], v[102:105]
	v_mfma_f32_16x16x32_bf16 v[94:97], v[178:181], v[204:207], v[94:97]
	v_mfma_f32_16x16x32_bf16 v[86:89], v[170:173], v[212:215], v[86:89]
	v_mfma_f32_16x16x32_bf16 v[78:81], v[178:181], v[212:215], v[78:81]
	v_mfma_f32_16x16x32_bf16 v[70:73], v[170:173], v[220:223], v[70:73]
	v_mfma_f32_16x16x32_bf16 v[66:69], v[178:181], v[220:223], v[66:69]
	s_setprio 0
	s_barrier
	s_add_i32 s70, s70, s55
	s_mov_b32 m0, s70
	ds_read_b128 v[182:185], v149 offset:16384
	ds_read_b128 v[186:189], v149 offset:17408
	ds_read_b128 v[190:193], v149 offset:18432
	ds_read_b128 v[204:207], v149 offset:19456
	ds_read_b128 v[208:211], v149 offset:20480
	ds_read_b128 v[212:215], v149 offset:21504
	ds_read_b128 v[216:219], v149 offset:22528
	ds_read_b128 v[220:223], v149 offset:23552
	global_load_lds_dwordx4 v0, s[50:51]
	s_add_i32 m0, s70, 0x2000
	s_add_u32 s70, s50, 0x80000
	s_addc_u32 s71, s51, 0
	s_add_i32 s74, s74, s55
	global_load_lds_dwordx4 v134, s[50:51]
	s_mov_b32 m0, s74
	s_nop 0
	global_load_lds_dwordx4 v0, s[70:71]
	s_add_i32 m0, s74, 0x2000
	s_nop 0
	global_load_lds_dwordx4 v134, s[70:71]
	s_mov_b32 m0, s31
	s_nop 0
	global_load_lds_dwordx4 v130, s[52:53]
	s_mov_b32 m0, s39
	s_nop 0
	global_load_lds_dwordx4 v132, s[52:53]
	s_waitcnt vmcnt(8)
	s_waitcnt lgkmcnt(0)
	s_barrier
	s_setprio 1
	s_waitcnt lgkmcnt(0)
	v_mfma_f32_16x16x32_bf16 v[62:65], v[150:153], v[182:185], v[62:65]
	v_mfma_f32_16x16x32_bf16 v[58:61], v[158:161], v[182:185], v[58:61]
	v_mfma_f32_16x16x32_bf16 v[50:53], v[150:153], v[190:193], v[50:53]
	v_mfma_f32_16x16x32_bf16 v[42:45], v[158:161], v[190:193], v[42:45]
	v_mfma_f32_16x16x32_bf16 v[34:37], v[150:153], v[208:211], v[34:37]
	v_mfma_f32_16x16x32_bf16 v[26:29], v[158:161], v[208:211], v[26:29]
	v_mfma_f32_16x16x32_bf16 v[18:21], v[150:153], v[216:219], v[18:21]
	v_mfma_f32_16x16x32_bf16 v[10:13], v[158:161], v[216:219], v[10:13]
	v_mfma_f32_16x16x32_bf16 v[62:65], v[154:157], v[186:189], v[62:65]
	v_mfma_f32_16x16x32_bf16 v[58:61], v[162:165], v[186:189], v[58:61]
	v_mfma_f32_16x16x32_bf16 v[50:53], v[154:157], v[204:207], v[50:53]
	v_mfma_f32_16x16x32_bf16 v[42:45], v[162:165], v[204:207], v[42:45]
	v_mfma_f32_16x16x32_bf16 v[34:37], v[154:157], v[212:215], v[34:37]
	v_mfma_f32_16x16x32_bf16 v[26:29], v[162:165], v[212:215], v[26:29]
	v_mfma_f32_16x16x32_bf16 v[18:21], v[154:157], v[220:223], v[18:21]
	v_mfma_f32_16x16x32_bf16 v[10:13], v[162:165], v[220:223], v[10:13]
	s_setprio 0
	s_setprio 1
	v_mfma_f32_16x16x32_bf16 v[54:57], v[166:169], v[182:185], v[54:57]
	v_mfma_f32_16x16x32_bf16 v[46:49], v[174:177], v[182:185], v[46:49]
	v_mfma_f32_16x16x32_bf16 v[38:41], v[166:169], v[190:193], v[38:41]
	v_mfma_f32_16x16x32_bf16 v[30:33], v[174:177], v[190:193], v[30:33]
	v_mfma_f32_16x16x32_bf16 v[22:25], v[166:169], v[208:211], v[22:25]
	v_mfma_f32_16x16x32_bf16 v[14:17], v[174:177], v[208:211], v[14:17]
	v_mfma_f32_16x16x32_bf16 v[6:9], v[166:169], v[216:219], v[6:9]
	v_mfma_f32_16x16x32_bf16 v[2:5], v[174:177], v[216:219], v[2:5]
	v_mfma_f32_16x16x32_bf16 v[54:57], v[170:173], v[186:189], v[54:57]
	v_mfma_f32_16x16x32_bf16 v[46:49], v[178:181], v[186:189], v[46:49]
	v_mfma_f32_16x16x32_bf16 v[38:41], v[170:173], v[204:207], v[38:41]
	v_mfma_f32_16x16x32_bf16 v[30:33], v[178:181], v[204:207], v[30:33]
	v_mfma_f32_16x16x32_bf16 v[22:25], v[170:173], v[212:215], v[22:25]
	v_mfma_f32_16x16x32_bf16 v[14:17], v[178:181], v[212:215], v[14:17]
	v_mfma_f32_16x16x32_bf16 v[6:9], v[170:173], v[220:223], v[6:9]
	v_mfma_f32_16x16x32_bf16 v[2:5], v[178:181], v[220:223], v[2:5]
	s_setprio 0
	s_barrier
	s_add_i32 s70, 0, 0x18000
	s_add_i32 s71, 0, 0x1c000
	ds_read_b128 v[150:153], v253 offset:32768
	ds_read_b128 v[154:157], v253 offset:33792
	ds_read_b128 v[158:161], v253 offset:34816
	ds_read_b128 v[162:165], v253 offset:35840
	ds_read_b128 v[166:169], v253 offset:49152
	ds_read_b128 v[170:173], v253 offset:50176
	ds_read_b128 v[174:177], v253 offset:51200
	ds_read_b128 v[178:181], v253 offset:52224
	s_add_u32 s52, s52, 0x80000
	s_addc_u32 s53, s53, 0
	s_mov_b32 m0, s56
	ds_read_b128 v[182:185], v149 offset:32768
	ds_read_b128 v[186:189], v149 offset:33792
	ds_read_b128 v[190:193], v149 offset:34816
	ds_read_b128 v[204:207], v149 offset:35840
	ds_read_b128 v[208:211], v149 offset:36864
	ds_read_b128 v[212:215], v149 offset:37888
	ds_read_b128 v[216:219], v149 offset:38912
	ds_read_b128 v[220:223], v149 offset:39936
	global_load_lds_dwordx4 v130, s[52:53]
	s_mov_b32 m0, s57
	s_nop 0
	global_load_lds_dwordx4 v132, s[52:53]
	s_waitcnt vmcnt(8)
	s_waitcnt lgkmcnt(0)
	s_barrier
	s_setprio 1
	s_waitcnt lgkmcnt(0)
	v_mfma_f32_16x16x32_bf16 v[126:129], v[150:153], v[182:185], v[126:129]
	v_mfma_f32_16x16x32_bf16 v[122:125], v[158:161], v[182:185], v[122:125]
	v_mfma_f32_16x16x32_bf16 v[114:117], v[150:153], v[190:193], v[114:117]
	v_mfma_f32_16x16x32_bf16 v[106:109], v[158:161], v[190:193], v[106:109]
	v_mfma_f32_16x16x32_bf16 v[98:101], v[150:153], v[208:211], v[98:101]
	v_mfma_f32_16x16x32_bf16 v[90:93], v[158:161], v[208:211], v[90:93]
	v_mfma_f32_16x16x32_bf16 v[82:85], v[150:153], v[216:219], v[82:85]
	v_mfma_f32_16x16x32_bf16 v[74:77], v[158:161], v[216:219], v[74:77]
	v_mfma_f32_16x16x32_bf16 v[126:129], v[154:157], v[186:189], v[126:129]
	v_mfma_f32_16x16x32_bf16 v[122:125], v[162:165], v[186:189], v[122:125]
	v_mfma_f32_16x16x32_bf16 v[114:117], v[154:157], v[204:207], v[114:117]
	v_mfma_f32_16x16x32_bf16 v[106:109], v[162:165], v[204:207], v[106:109]
	v_mfma_f32_16x16x32_bf16 v[98:101], v[154:157], v[212:215], v[98:101]
	v_mfma_f32_16x16x32_bf16 v[90:93], v[162:165], v[212:215], v[90:93]
	v_mfma_f32_16x16x32_bf16 v[82:85], v[154:157], v[220:223], v[82:85]
	v_mfma_f32_16x16x32_bf16 v[74:77], v[162:165], v[220:223], v[74:77]
	s_setprio 0
	s_setprio 1
	v_mfma_f32_16x16x32_bf16 v[118:121], v[166:169], v[182:185], v[118:121]
	v_mfma_f32_16x16x32_bf16 v[110:113], v[174:177], v[182:185], v[110:113]
	v_mfma_f32_16x16x32_bf16 v[102:105], v[166:169], v[190:193], v[102:105]
	v_mfma_f32_16x16x32_bf16 v[94:97], v[174:177], v[190:193], v[94:97]
	v_mfma_f32_16x16x32_bf16 v[86:89], v[166:169], v[208:211], v[86:89]
	v_mfma_f32_16x16x32_bf16 v[78:81], v[174:177], v[208:211], v[78:81]
	v_mfma_f32_16x16x32_bf16 v[70:73], v[166:169], v[216:219], v[70:73]
	v_mfma_f32_16x16x32_bf16 v[66:69], v[174:177], v[216:219], v[66:69]
	v_mfma_f32_16x16x32_bf16 v[118:121], v[170:173], v[186:189], v[118:121]
	v_mfma_f32_16x16x32_bf16 v[110:113], v[178:181], v[186:189], v[110:113]
	v_mfma_f32_16x16x32_bf16 v[102:105], v[170:173], v[204:207], v[102:105]
	v_mfma_f32_16x16x32_bf16 v[94:97], v[178:181], v[204:207], v[94:97]
	v_mfma_f32_16x16x32_bf16 v[86:89], v[170:173], v[212:215], v[86:89]
	v_mfma_f32_16x16x32_bf16 v[78:81], v[178:181], v[212:215], v[78:81]
	v_mfma_f32_16x16x32_bf16 v[70:73], v[170:173], v[220:223], v[70:73]
	v_mfma_f32_16x16x32_bf16 v[66:69], v[178:181], v[220:223], v[66:69]
	s_setprio 0
	s_barrier
	s_add_u32 s100, s52, 0xfff80080
	s_addc_u32 s101, s53, -1
	s_add_u32 s98, s50, 0x80
	s_addc_u32 s99, s51, 0
	s_add_i32 s52, s70, s55
	s_mov_b32 m0, s52
	ds_read_b128 v[182:185], v149 offset:49152
	ds_read_b128 v[186:189], v149 offset:50176
	ds_read_b128 v[190:193], v149 offset:51200
	ds_read_b128 v[204:207], v149 offset:52224
	ds_read_b128 v[208:211], v149 offset:53248
	ds_read_b128 v[212:215], v149 offset:54272
	ds_read_b128 v[216:219], v149 offset:55296
	ds_read_b128 v[220:223], v149 offset:56320
	global_load_lds_dwordx4 v0, s[98:99]
	s_add_i32 m0, s52, 0x2000
	s_add_u32 s50, s50, 0x80080
	s_addc_u32 s51, s51, 0
	s_add_i32 s52, s71, s55
	global_load_lds_dwordx4 v134, s[98:99]
	s_mov_b32 m0, s52
	s_nop 0
	global_load_lds_dwordx4 v0, s[50:51]
	s_add_i32 m0, s52, 0x2000
	s_nop 0
	global_load_lds_dwordx4 v134, s[50:51]
	s_mov_b32 m0, s61
	s_nop 0
	global_load_lds_dwordx4 v130, s[100:101]
	s_mov_b32 m0, s62
	s_nop 0
	global_load_lds_dwordx4 v132, s[100:101]
	s_waitcnt vmcnt(8)
	s_waitcnt lgkmcnt(0)
	s_barrier
	s_setprio 1
	s_waitcnt lgkmcnt(0)
	v_mfma_f32_16x16x32_bf16 v[62:65], v[150:153], v[182:185], v[62:65]
	v_mfma_f32_16x16x32_bf16 v[58:61], v[158:161], v[182:185], v[58:61]
	v_mfma_f32_16x16x32_bf16 v[50:53], v[150:153], v[190:193], v[50:53]
	v_mfma_f32_16x16x32_bf16 v[42:45], v[158:161], v[190:193], v[42:45]
	v_mfma_f32_16x16x32_bf16 v[34:37], v[150:153], v[208:211], v[34:37]
	v_mfma_f32_16x16x32_bf16 v[26:29], v[158:161], v[208:211], v[26:29]
	v_mfma_f32_16x16x32_bf16 v[18:21], v[150:153], v[216:219], v[18:21]
	v_mfma_f32_16x16x32_bf16 v[10:13], v[158:161], v[216:219], v[10:13]
	v_mfma_f32_16x16x32_bf16 v[62:65], v[154:157], v[186:189], v[62:65]
	v_mfma_f32_16x16x32_bf16 v[58:61], v[162:165], v[186:189], v[58:61]
	v_mfma_f32_16x16x32_bf16 v[50:53], v[154:157], v[204:207], v[50:53]
	v_mfma_f32_16x16x32_bf16 v[42:45], v[162:165], v[204:207], v[42:45]
	v_mfma_f32_16x16x32_bf16 v[34:37], v[154:157], v[212:215], v[34:37]
	v_mfma_f32_16x16x32_bf16 v[26:29], v[162:165], v[212:215], v[26:29]
	v_mfma_f32_16x16x32_bf16 v[18:21], v[154:157], v[220:223], v[18:21]
	v_mfma_f32_16x16x32_bf16 v[10:13], v[162:165], v[220:223], v[10:13]
	s_setprio 0
	s_setprio 1
	v_mfma_f32_16x16x32_bf16 v[54:57], v[166:169], v[182:185], v[54:57]
	v_mfma_f32_16x16x32_bf16 v[46:49], v[174:177], v[182:185], v[46:49]
	v_mfma_f32_16x16x32_bf16 v[38:41], v[166:169], v[190:193], v[38:41]
	v_mfma_f32_16x16x32_bf16 v[30:33], v[174:177], v[190:193], v[30:33]
	v_mfma_f32_16x16x32_bf16 v[22:25], v[166:169], v[208:211], v[22:25]
	v_mfma_f32_16x16x32_bf16 v[14:17], v[174:177], v[208:211], v[14:17]
	v_mfma_f32_16x16x32_bf16 v[6:9], v[166:169], v[216:219], v[6:9]
	v_mfma_f32_16x16x32_bf16 v[2:5], v[174:177], v[216:219], v[2:5]
	v_mfma_f32_16x16x32_bf16 v[54:57], v[170:173], v[186:189], v[54:57]
	v_mfma_f32_16x16x32_bf16 v[46:49], v[178:181], v[186:189], v[46:49]
	v_mfma_f32_16x16x32_bf16 v[38:41], v[170:173], v[204:207], v[38:41]
	v_mfma_f32_16x16x32_bf16 v[30:33], v[178:181], v[204:207], v[30:33]
	v_mfma_f32_16x16x32_bf16 v[22:25], v[170:173], v[212:215], v[22:25]
	v_mfma_f32_16x16x32_bf16 v[14:17], v[178:181], v[212:215], v[14:17]
	v_mfma_f32_16x16x32_bf16 v[6:9], v[170:173], v[220:223], v[6:9]
	v_mfma_f32_16x16x32_bf16 v[2:5], v[178:181], v[220:223], v[2:5]
	s_setprio 0
	s_barrier
	s_add_u32 s42, s42, 0x100
	s_addc_u32 s43, s43, 0
	s_add_u32 s45, s45, 0x100
	s_addc_u32 s58, s58, 0
	s_cmp_ge_u32 s59, s33
	s_mov_b32 s50, s59
	s_cbranch_scc0 .LBB0_201
	s_and_b64 vcc, exec, s[20:21]
	s_cbranch_vccz .LBB0_206
	s_barrier
	s_cmp_ge_i32 s30, s17
	s_mov_b64 s[42:43], -1
	s_cbranch_scc1 .LBB0_207

.LBB0_344:
	s_ashr_i32 s13, s12, 31
	s_lshl_b64 s[14:15], s[12:13], 18
	s_add_u32 s14, s17, s14
	s_addc_u32 s15, s18, s15
	s_and_b64 s[20:21], s[4:5], exec
	s_cselect_b32 s13, s15, s25
	s_cselect_b32 s40, s14, s24
	s_ashr_i32 s11, s10, 31
	s_lshl_b64 s[20:21], s[10:11], 18
	s_add_u32 s20, s19, s20
	s_addc_u32 s21, s28, s21
	s_and_b64 s[30:31], s[4:5], exec
	s_cselect_b32 s11, s21, s27
	s_cselect_b32 s41, s20, s26
	s_add_u32 s24, s24, 0x20080
	s_addc_u32 s25, s25, 0
	s_add_u32 s43, s26, 0x100
	v_mov_b32_e32 v2, 0
	s_addc_u32 s44, s27, 0
	s_mov_b32 s45, -2
	v_mov_b32_e32 v3, v2
	v_mov_b32_e32 v4, v2
	v_mov_b32_e32 v5, v2
	v_mov_b32_e32 v6, v2
	v_mov_b32_e32 v7, v2
	v_mov_b32_e32 v8, v2
	v_mov_b32_e32 v9, v2
	v_mov_b32_e32 v14, v2
	v_mov_b32_e32 v15, v2
	v_mov_b32_e32 v16, v2
	v_mov_b32_e32 v17, v2
	v_mov_b32_e32 v22, v2
	v_mov_b32_e32 v23, v2
	v_mov_b32_e32 v24, v2
	v_mov_b32_e32 v25, v2
	v_mov_b32_e32 v30, v2
	v_mov_b32_e32 v31, v2
	v_mov_b32_e32 v32, v2
	v_mov_b32_e32 v33, v2
	v_mov_b32_e32 v38, v2
	v_mov_b32_e32 v39, v2
	v_mov_b32_e32 v40, v2
	v_mov_b32_e32 v41, v2
	v_mov_b32_e32 v46, v2
	v_mov_b32_e32 v47, v2
	v_mov_b32_e32 v48, v2
	v_mov_b32_e32 v49, v2
	v_mov_b32_e32 v54, v2
	v_mov_b32_e32 v55, v2
	v_mov_b32_e32 v56, v2
	v_mov_b32_e32 v57, v2
	v_mov_b32_e32 v10, v2
	v_mov_b32_e32 v11, v2
	v_mov_b32_e32 v12, v2
	v_mov_b32_e32 v13, v2
	v_mov_b32_e32 v18, v2
	v_mov_b32_e32 v19, v2
	v_mov_b32_e32 v20, v2
	v_mov_b32_e32 v21, v2
	v_mov_b32_e32 v26, v2
	v_mov_b32_e32 v27, v2
	v_mov_b32_e32 v28, v2
	v_mov_b32_e32 v29, v2
	v_mov_b32_e32 v34, v2
	v_mov_b32_e32 v35, v2
	v_mov_b32_e32 v36, v2
	v_mov_b32_e32 v37, v2
	v_mov_b32_e32 v42, v2
	v_mov_b32_e32 v43, v2
	v_mov_b32_e32 v44, v2
	v_mov_b32_e32 v45, v2
	v_mov_b32_e32 v50, v2
	v_mov_b32_e32 v51, v2
	v_mov_b32_e32 v52, v2
	v_mov_b32_e32 v53, v2
	v_mov_b32_e32 v58, v2
	v_mov_b32_e32 v59, v2
	v_mov_b32_e32 v60, v2
	v_mov_b32_e32 v61, v2
	v_mov_b32_e32 v62, v2
	v_mov_b32_e32 v63, v2
	v_mov_b32_e32 v64, v2
	v_mov_b32_e32 v65, v2
	v_mov_b32_e32 v66, v2
	v_mov_b32_e32 v67, v2
	v_mov_b32_e32 v68, v2
	v_mov_b32_e32 v69, v2
	v_mov_b32_e32 v70, v2
	v_mov_b32_e32 v71, v2
	v_mov_b32_e32 v72, v2
	v_mov_b32_e32 v73, v2
	v_mov_b32_e32 v78, v2
	v_mov_b32_e32 v79, v2
	v_mov_b32_e32 v80, v2
	v_mov_b32_e32 v81, v2
	v_mov_b32_e32 v86, v2
	v_mov_b32_e32 v87, v2
	v_mov_b32_e32 v88, v2
	v_mov_b32_e32 v89, v2
	v_mov_b32_e32 v94, v2
	v_mov_b32_e32 v95, v2
	v_mov_b32_e32 v96, v2
	v_mov_b32_e32 v97, v2
	v_mov_b32_e32 v102, v2
	v_mov_b32_e32 v103, v2
	v_mov_b32_e32 v104, v2
	v_mov_b32_e32 v105, v2
	v_mov_b32_e32 v110, v2
	v_mov_b32_e32 v111, v2
	v_mov_b32_e32 v112, v2
	v_mov_b32_e32 v113, v2
	v_mov_b32_e32 v118, v2
	v_mov_b32_e32 v119, v2
	v_mov_b32_e32 v120, v2
	v_mov_b32_e32 v121, v2
	v_mov_b32_e32 v74, v2
	v_mov_b32_e32 v75, v2
	v_mov_b32_e32 v76, v2
	v_mov_b32_e32 v77, v2
	v_mov_b32_e32 v82, v2
	v_mov_b32_e32 v83, v2
	v_mov_b32_e32 v84, v2
	v_mov_b32_e32 v85, v2
	v_mov_b32_e32 v90, v2
	v_mov_b32_e32 v91, v2
	v_mov_b32_e32 v92, v2
	v_mov_b32_e32 v93, v2
	v_mov_b32_e32 v98, v2
	v_mov_b32_e32 v99, v2
	v_mov_b32_e32 v100, v2
	v_mov_b32_e32 v101, v2
	v_mov_b32_e32 v106, v2
	v_mov_b32_e32 v107, v2
	v_mov_b32_e32 v108, v2
	v_mov_b32_e32 v109, v2
	v_mov_b32_e32 v114, v2
	v_mov_b32_e32 v115, v2
	v_mov_b32_e32 v116, v2
	v_mov_b32_e32 v117, v2
	v_mov_b32_e32 v122, v2
	v_mov_b32_e32 v123, v2
	v_mov_b32_e32 v124, v2
	v_mov_b32_e32 v125, v2
	v_mov_b32_e32 v126, v2
	v_mov_b32_e32 v127, v2
	v_mov_b32_e32 v128, v2
	v_mov_b32_e32 v129, v2
	v_add_u32_e32 v253, 0x10000, v154
.LBB0_345:
	s_add_u32 s26, s24, 0xfffe0080
	s_addc_u32 s27, s25, -1
	s_add_i32 s46, 0, 0x10000
	s_cmp_eq_u32 s45, 4
	s_cselect_b32 s31, s13, s27
	s_cselect_b32 s30, s40, s26
	s_cselect_b32 s27, s11, s44
	s_cselect_b32 s26, s41, s43
	s_add_i32 s52, 0, 0x14000
	ds_read_b128 v[158:161], v253
	ds_read_b128 v[162:165], v253 offset:1024
	ds_read_b128 v[166:169], v253 offset:2048
	ds_read_b128 v[170:173], v253 offset:3072
	ds_read_b128 v[174:177], v253 offset:16384
	ds_read_b128 v[178:181], v253 offset:17408
	ds_read_b128 v[182:185], v253 offset:18432
	ds_read_b128 v[186:189], v253 offset:19456
	s_add_i32 m0, s23, 0xc000
	ds_read_b128 v[190:193], v156
	ds_read_b128 v[204:207], v156 offset:1024
	ds_read_b128 v[208:211], v156 offset:2048
	ds_read_b128 v[212:215], v156 offset:3072
	ds_read_b128 v[216:219], v156 offset:4096
	ds_read_b128 v[220:223], v156 offset:5120
	ds_read_b128 v[224:227], v156 offset:6144
	ds_read_b128 v[228:231], v156 offset:7168
	global_load_lds_dwordx4 v136, s[24:25]
	s_add_i32 m0, s23, 0xe000
	s_nop 0
	global_load_lds_dwordx4 v138, s[24:25]
	s_waitcnt vmcnt(8)
	s_waitcnt lgkmcnt(0)
	s_barrier
	s_setprio 1
	s_waitcnt lgkmcnt(0)
	v_mfma_f32_16x16x32_bf16 v[126:129], v[158:161], v[190:193], v[126:129]
	v_mfma_f32_16x16x32_bf16 v[122:125], v[166:169], v[190:193], v[122:125]
	v_mfma_f32_16x16x32_bf16 v[114:117], v[158:161], v[208:211], v[114:117]
	v_mfma_f32_16x16x32_bf16 v[106:109], v[166:169], v[208:211], v[106:109]
	v_mfma_f32_16x16x32_bf16 v[98:101], v[158:161], v[216:219], v[98:101]
	v_mfma_f32_16x16x32_bf16 v[90:93], v[166:169], v[216:219], v[90:93]
	v_mfma_f32_16x16x32_bf16 v[82:85], v[158:161], v[224:227], v[82:85]
	v_mfma_f32_16x16x32_bf16 v[74:77], v[166:169], v[224:227], v[74:77]
	v_mfma_f32_16x16x32_bf16 v[126:129], v[162:165], v[204:207], v[126:129]
	v_mfma_f32_16x16x32_bf16 v[122:125], v[170:173], v[204:207], v[122:125]
	v_mfma_f32_16x16x32_bf16 v[114:117], v[162:165], v[212:215], v[114:117]
	v_mfma_f32_16x16x32_bf16 v[106:109], v[170:173], v[212:215], v[106:109]
	v_mfma_f32_16x16x32_bf16 v[98:101], v[162:165], v[220:223], v[98:101]
	v_mfma_f32_16x16x32_bf16 v[90:93], v[170:173], v[220:223], v[90:93]
	v_mfma_f32_16x16x32_bf16 v[82:85], v[162:165], v[228:231], v[82:85]
	v_mfma_f32_16x16x32_bf16 v[74:77], v[170:173], v[228:231], v[74:77]
	s_setprio 0
	s_setprio 1
	v_mfma_f32_16x16x32_bf16 v[118:121], v[174:177], v[190:193], v[118:121]
	v_mfma_f32_16x16x32_bf16 v[110:113], v[182:185], v[190:193], v[110:113]
	v_mfma_f32_16x16x32_bf16 v[102:105], v[174:177], v[208:211], v[102:105]
	v_mfma_f32_16x16x32_bf16 v[94:97], v[182:185], v[208:211], v[94:97]
	v_mfma_f32_16x16x32_bf16 v[86:89], v[174:177], v[216:219], v[86:89]
	v_mfma_f32_16x16x32_bf16 v[78:81], v[182:185], v[216:219], v[78:81]
	v_mfma_f32_16x16x32_bf16 v[70:73], v[174:177], v[224:227], v[70:73]
	v_mfma_f32_16x16x32_bf16 v[66:69], v[182:185], v[224:227], v[66:69]
	v_mfma_f32_16x16x32_bf16 v[118:121], v[178:181], v[204:207], v[118:121]
	v_mfma_f32_16x16x32_bf16 v[110:113], v[186:189], v[204:207], v[110:113]
	v_mfma_f32_16x16x32_bf16 v[102:105], v[178:181], v[212:215], v[102:105]
	v_mfma_f32_16x16x32_bf16 v[94:97], v[186:189], v[212:215], v[94:97]
	v_mfma_f32_16x16x32_bf16 v[86:89], v[178:181], v[220:223], v[86:89]
	v_mfma_f32_16x16x32_bf16 v[78:81], v[186:189], v[220:223], v[78:81]
	v_mfma_f32_16x16x32_bf16 v[70:73], v[178:181], v[228:231], v[70:73]
	v_mfma_f32_16x16x32_bf16 v[66:69], v[186:189], v[228:231], v[66:69]
	s_setprio 0
	s_barrier
	s_add_i32 s46, s46, s29
	s_mov_b32 m0, s46
	ds_read_b128 v[190:193], v156 offset:16384
	ds_read_b128 v[204:207], v156 offset:17408
	ds_read_b128 v[208:211], v156 offset:18432
	ds_read_b128 v[212:215], v156 offset:19456
	ds_read_b128 v[216:219], v156 offset:20480
	ds_read_b128 v[220:223], v156 offset:21504
	ds_read_b128 v[224:227], v156 offset:22528
	ds_read_b128 v[228:231], v156 offset:23552
	global_load_lds_dwordx4 v0, s[26:27]
	s_add_i32 m0, s46, 0x2000
	s_add_u32 s50, s26, 0x20000
	s_addc_u32 s51, s27, 0
	s_add_i32 s46, s52, s29
	global_load_lds_dwordx4 v130, s[26:27]
	s_mov_b32 m0, s46
	s_nop 0
	global_load_lds_dwordx4 v0, s[50:51]
	s_add_i32 m0, s46, 0x2000
	s_nop 0
	global_load_lds_dwordx4 v130, s[50:51]
	s_mov_b32 m0, s23
	s_nop 0
	global_load_lds_dwordx4 v134, s[30:31]
	s_mov_b32 m0, s35
	s_nop 0
	global_load_lds_dwordx4 v132, s[30:31]
	s_waitcnt vmcnt(8)
	s_waitcnt lgkmcnt(0)
	s_barrier
	s_setprio 1
	s_waitcnt lgkmcnt(0)
	v_mfma_f32_16x16x32_bf16 v[62:65], v[158:161], v[190:193], v[62:65]
	v_mfma_f32_16x16x32_bf16 v[58:61], v[166:169], v[190:193], v[58:61]
	v_mfma_f32_16x16x32_bf16 v[50:53], v[158:161], v[208:211], v[50:53]
	v_mfma_f32_16x16x32_bf16 v[42:45], v[166:169], v[208:211], v[42:45]
	v_mfma_f32_16x16x32_bf16 v[34:37], v[158:161], v[216:219], v[34:37]
	v_mfma_f32_16x16x32_bf16 v[26:29], v[166:169], v[216:219], v[26:29]
	v_mfma_f32_16x16x32_bf16 v[18:21], v[158:161], v[224:227], v[18:21]
	v_mfma_f32_16x16x32_bf16 v[10:13], v[166:169], v[224:227], v[10:13]
	v_mfma_f32_16x16x32_bf16 v[62:65], v[162:165], v[204:207], v[62:65]
	v_mfma_f32_16x16x32_bf16 v[58:61], v[170:173], v[204:207], v[58:61]
	v_mfma_f32_16x16x32_bf16 v[50:53], v[162:165], v[212:215], v[50:53]
	v_mfma_f32_16x16x32_bf16 v[42:45], v[170:173], v[212:215], v[42:45]
	v_mfma_f32_16x16x32_bf16 v[34:37], v[162:165], v[220:223], v[34:37]
	v_mfma_f32_16x16x32_bf16 v[26:29], v[170:173], v[220:223], v[26:29]
	v_mfma_f32_16x16x32_bf16 v[18:21], v[162:165], v[228:231], v[18:21]
	v_mfma_f32_16x16x32_bf16 v[10:13], v[170:173], v[228:231], v[10:13]
	s_setprio 0
	s_setprio 1
	v_mfma_f32_16x16x32_bf16 v[54:57], v[174:177], v[190:193], v[54:57]
	v_mfma_f32_16x16x32_bf16 v[46:49], v[182:185], v[190:193], v[46:49]
	v_mfma_f32_16x16x32_bf16 v[38:41], v[174:177], v[208:211], v[38:41]
	v_mfma_f32_16x16x32_bf16 v[30:33], v[182:185], v[208:211], v[30:33]
	v_mfma_f32_16x16x32_bf16 v[22:25], v[174:177], v[216:219], v[22:25]
	v_mfma_f32_16x16x32_bf16 v[14:17], v[182:185], v[216:219], v[14:17]
	v_mfma_f32_16x16x32_bf16 v[6:9], v[174:177], v[224:227], v[6:9]
	v_mfma_f32_16x16x32_bf16 v[2:5], v[182:185], v[224:227], v[2:5]
	v_mfma_f32_16x16x32_bf16 v[54:57], v[178:181], v[204:207], v[54:57]
	v_mfma_f32_16x16x32_bf16 v[46:49], v[186:189], v[204:207], v[46:49]
	v_mfma_f32_16x16x32_bf16 v[38:41], v[178:181], v[212:215], v[38:41]
	v_mfma_f32_16x16x32_bf16 v[30:33], v[186:189], v[212:215], v[30:33]
	v_mfma_f32_16x16x32_bf16 v[22:25], v[178:181], v[220:223], v[22:25]
	v_mfma_f32_16x16x32_bf16 v[14:17], v[186:189], v[220:223], v[14:17]
	v_mfma_f32_16x16x32_bf16 v[6:9], v[178:181], v[228:231], v[6:9]
	v_mfma_f32_16x16x32_bf16 v[2:5], v[186:189], v[228:231], v[2:5]
	s_setprio 0
	s_barrier
	s_add_i32 s46, 0, 0x18000
	s_add_i32 s50, 0, 0x1c000
	ds_read_b128 v[158:161], v253 offset:32768
	ds_read_b128 v[162:165], v253 offset:33792
	ds_read_b128 v[166:169], v253 offset:34816
	ds_read_b128 v[170:173], v253 offset:35840
	ds_read_b128 v[174:177], v253 offset:49152
	ds_read_b128 v[178:181], v253 offset:50176
	ds_read_b128 v[182:185], v253 offset:51200
	ds_read_b128 v[186:189], v253 offset:52224
	s_add_u32 s30, s30, 0x20000
	s_addc_u32 s31, s31, 0
	s_mov_b32 m0, s36
	ds_read_b128 v[190:193], v156 offset:32768
	ds_read_b128 v[204:207], v156 offset:33792
	ds_read_b128 v[208:211], v156 offset:34816
	ds_read_b128 v[212:215], v156 offset:35840
	ds_read_b128 v[216:219], v156 offset:36864
	ds_read_b128 v[220:223], v156 offset:37888
	ds_read_b128 v[224:227], v156 offset:38912
	ds_read_b128 v[228:231], v156 offset:39936
	global_load_lds_dwordx4 v134, s[30:31]
	s_mov_b32 m0, s37
	s_nop 0
	global_load_lds_dwordx4 v132, s[30:31]
	s_waitcnt vmcnt(8)
	s_waitcnt lgkmcnt(0)
	s_barrier
	s_setprio 1
	s_waitcnt lgkmcnt(0)
	v_mfma_f32_16x16x32_bf16 v[126:129], v[158:161], v[190:193], v[126:129]
	v_mfma_f32_16x16x32_bf16 v[122:125], v[166:169], v[190:193], v[122:125]
	v_mfma_f32_16x16x32_bf16 v[114:117], v[158:161], v[208:211], v[114:117]
	v_mfma_f32_16x16x32_bf16 v[106:109], v[166:169], v[208:211], v[106:109]
	v_mfma_f32_16x16x32_bf16 v[98:101], v[158:161], v[216:219], v[98:101]
	v_mfma_f32_16x16x32_bf16 v[90:93], v[166:169], v[216:219], v[90:93]
	v_mfma_f32_16x16x32_bf16 v[82:85], v[158:161], v[224:227], v[82:85]
	v_mfma_f32_16x16x32_bf16 v[74:77], v[166:169], v[224:227], v[74:77]
	v_mfma_f32_16x16x32_bf16 v[126:129], v[162:165], v[204:207], v[126:129]
	v_mfma_f32_16x16x32_bf16 v[122:125], v[170:173], v[204:207], v[122:125]
	v_mfma_f32_16x16x32_bf16 v[114:117], v[162:165], v[212:215], v[114:117]
	v_mfma_f32_16x16x32_bf16 v[106:109], v[170:173], v[212:215], v[106:109]
	v_mfma_f32_16x16x32_bf16 v[98:101], v[162:165], v[220:223], v[98:101]
	v_mfma_f32_16x16x32_bf16 v[90:93], v[170:173], v[220:223], v[90:93]
	v_mfma_f32_16x16x32_bf16 v[82:85], v[162:165], v[228:231], v[82:85]
	v_mfma_f32_16x16x32_bf16 v[74:77], v[170:173], v[228:231], v[74:77]
	s_setprio 0
	s_setprio 1
	v_mfma_f32_16x16x32_bf16 v[118:121], v[174:177], v[190:193], v[118:121]
	v_mfma_f32_16x16x32_bf16 v[110:113], v[182:185], v[190:193], v[110:113]
	v_mfma_f32_16x16x32_bf16 v[102:105], v[174:177], v[208:211], v[102:105]
	v_mfma_f32_16x16x32_bf16 v[94:97], v[182:185], v[208:211], v[94:97]
	v_mfma_f32_16x16x32_bf16 v[86:89], v[174:177], v[216:219], v[86:89]
	v_mfma_f32_16x16x32_bf16 v[78:81], v[182:185], v[216:219], v[78:81]
	v_mfma_f32_16x16x32_bf16 v[70:73], v[174:177], v[224:227], v[70:73]
	v_mfma_f32_16x16x32_bf16 v[66:69], v[182:185], v[224:227], v[66:69]
	v_mfma_f32_16x16x32_bf16 v[118:121], v[178:181], v[204:207], v[118:121]
	v_mfma_f32_16x16x32_bf16 v[110:113], v[186:189], v[204:207], v[110:113]
	v_mfma_f32_16x16x32_bf16 v[102:105], v[178:181], v[212:215], v[102:105]
	v_mfma_f32_16x16x32_bf16 v[94:97], v[186:189], v[212:215], v[94:97]
	v_mfma_f32_16x16x32_bf16 v[86:89], v[178:181], v[220:223], v[86:89]
	v_mfma_f32_16x16x32_bf16 v[78:81], v[186:189], v[220:223], v[78:81]
	v_mfma_f32_16x16x32_bf16 v[70:73], v[178:181], v[228:231], v[70:73]
	v_mfma_f32_16x16x32_bf16 v[66:69], v[186:189], v[228:231], v[66:69]
	s_setprio 0
	s_barrier
	s_add_u32 s100, s30, 0xfffe0080
	s_addc_u32 s101, s31, -1
	s_add_u32 s98, s26, 0x80
	s_addc_u32 s99, s27, 0
	s_add_i32 s30, s46, s29
	s_mov_b32 m0, s30
	ds_read_b128 v[190:193], v156 offset:49152
	ds_read_b128 v[204:207], v156 offset:50176
	ds_read_b128 v[208:211], v156 offset:51200
	ds_read_b128 v[212:215], v156 offset:52224
	ds_read_b128 v[216:219], v156 offset:53248
	ds_read_b128 v[220:223], v156 offset:54272
	ds_read_b128 v[224:227], v156 offset:55296
	ds_read_b128 v[228:231], v156 offset:56320
	global_load_lds_dwordx4 v0, s[98:99]
	s_add_i32 m0, s30, 0x2000
	s_add_u32 s26, s26, 0x20080
	s_addc_u32 s27, s27, 0
	s_add_i32 s30, s50, s29
	global_load_lds_dwordx4 v130, s[98:99]
	s_mov_b32 m0, s30
	s_nop 0
	global_load_lds_dwordx4 v0, s[26:27]
	s_add_i32 m0, s30, 0x2000
	s_nop 0
	global_load_lds_dwordx4 v130, s[26:27]
	s_mov_b32 m0, s38
	s_nop 0
	global_load_lds_dwordx4 v134, s[100:101]
	s_mov_b32 m0, s39
	s_nop 0
	global_load_lds_dwordx4 v132, s[100:101]
	s_waitcnt vmcnt(8)
	s_waitcnt lgkmcnt(0)
	s_barrier
	s_setprio 1
	s_waitcnt lgkmcnt(0)
	v_mfma_f32_16x16x32_bf16 v[62:65], v[158:161], v[190:193], v[62:65]
	v_mfma_f32_16x16x32_bf16 v[58:61], v[166:169], v[190:193], v[58:61]
	v_mfma_f32_16x16x32_bf16 v[50:53], v[158:161], v[208:211], v[50:53]
	v_mfma_f32_16x16x32_bf16 v[42:45], v[166:169], v[208:211], v[42:45]
	v_mfma_f32_16x16x32_bf16 v[34:37], v[158:161], v[216:219], v[34:37]
	v_mfma_f32_16x16x32_bf16 v[26:29], v[166:169], v[216:219], v[26:29]
	v_mfma_f32_16x16x32_bf16 v[18:21], v[158:161], v[224:227], v[18:21]
	v_mfma_f32_16x16x32_bf16 v[10:13], v[166:169], v[224:227], v[10:13]
	v_mfma_f32_16x16x32_bf16 v[62:65], v[162:165], v[204:207], v[62:65]
	v_mfma_f32_16x16x32_bf16 v[58:61], v[170:173], v[204:207], v[58:61]
	v_mfma_f32_16x16x32_bf16 v[50:53], v[162:165], v[212:215], v[50:53]
	v_mfma_f32_16x16x32_bf16 v[42:45], v[170:173], v[212:215], v[42:45]
	v_mfma_f32_16x16x32_bf16 v[34:37], v[162:165], v[220:223], v[34:37]
	v_mfma_f32_16x16x32_bf16 v[26:29], v[170:173], v[220:223], v[26:29]
	v_mfma_f32_16x16x32_bf16 v[18:21], v[162:165], v[228:231], v[18:21]
	v_mfma_f32_16x16x32_bf16 v[10:13], v[170:173], v[228:231], v[10:13]
	s_setprio 0
	s_setprio 1
	v_mfma_f32_16x16x32_bf16 v[54:57], v[174:177], v[190:193], v[54:57]
	v_mfma_f32_16x16x32_bf16 v[46:49], v[182:185], v[190:193], v[46:49]
	v_mfma_f32_16x16x32_bf16 v[38:41], v[174:177], v[208:211], v[38:41]
	v_mfma_f32_16x16x32_bf16 v[30:33], v[182:185], v[208:211], v[30:33]
	v_mfma_f32_16x16x32_bf16 v[22:25], v[174:177], v[216:219], v[22:25]
	v_mfma_f32_16x16x32_bf16 v[14:17], v[182:185], v[216:219], v[14:17]
	v_mfma_f32_16x16x32_bf16 v[6:9], v[174:177], v[224:227], v[6:9]
	v_mfma_f32_16x16x32_bf16 v[2:5], v[182:185], v[224:227], v[2:5]
	v_mfma_f32_16x16x32_bf16 v[54:57], v[178:181], v[204:207], v[54:57]
	v_mfma_f32_16x16x32_bf16 v[46:49], v[186:189], v[204:207], v[46:49]
	v_mfma_f32_16x16x32_bf16 v[38:41], v[178:181], v[212:215], v[38:41]
	v_mfma_f32_16x16x32_bf16 v[30:33], v[186:189], v[212:215], v[30:33]
	v_mfma_f32_16x16x32_bf16 v[22:25], v[178:181], v[220:223], v[22:25]
	v_mfma_f32_16x16x32_bf16 v[14:17], v[186:189], v[220:223], v[14:17]
	v_mfma_f32_16x16x32_bf16 v[6:9], v[178:181], v[228:231], v[6:9]
	v_mfma_f32_16x16x32_bf16 v[2:5], v[186:189], v[228:231], v[2:5]
	s_setprio 0
	s_barrier
	s_add_i32 s45, s45, 2
	s_add_u32 s24, s24, 0x100
	s_addc_u32 s25, s25, 0
	s_add_u32 s43, s43, 0x100
	s_addc_u32 s44, s44, 0
	s_cmp_gt_u32 s45, 5
	s_cbranch_scc0 .LBB0_345
	s_and_b64 vcc, exec, s[8:9]
	s_cbranch_vccz .LBB0_348
	s_barrier

.LBB0_360:
	s_ashr_i32 s11, s10, 31
	s_lshl_b64 s[12:13], s[10:11], 17
	s_add_u32 s12, s28, s12
	s_addc_u32 s13, s29, s13
	s_and_b64 s[14:15], s[4:5], exec
	s_cselect_b32 s11, s13, s25
	s_cselect_b32 s40, s12, s24
	s_ashr_i32 s9, s8, 31
	s_lshl_b64 s[14:15], s[8:9], 17
	s_add_u32 s14, s17, s14
	s_addc_u32 s15, s18, s15
	s_and_b64 s[26:27], s[4:5], exec
	v_mov_b32_e32 v2, 0
	s_cselect_b32 s9, s15, s23
	s_cselect_b32 s41, s14, s22
	s_mov_b32 s36, 0
	s_mov_b64 s[26:27], -1
	s_mov_b64 s[30:31], 0
	v_mov_b32_e32 v3, v2
	v_mov_b32_e32 v4, v2
	v_mov_b32_e32 v5, v2
	v_mov_b32_e32 v6, v2
	v_mov_b32_e32 v7, v2
	v_mov_b32_e32 v8, v2
	v_mov_b32_e32 v9, v2
	v_mov_b32_e32 v14, v2
	v_mov_b32_e32 v15, v2
	v_mov_b32_e32 v16, v2
	v_mov_b32_e32 v17, v2
	v_mov_b32_e32 v22, v2
	v_mov_b32_e32 v23, v2
	v_mov_b32_e32 v24, v2
	v_mov_b32_e32 v25, v2
	v_mov_b32_e32 v30, v2
	v_mov_b32_e32 v31, v2
	v_mov_b32_e32 v32, v2
	v_mov_b32_e32 v33, v2
	v_mov_b32_e32 v38, v2
	v_mov_b32_e32 v39, v2
	v_mov_b32_e32 v40, v2
	v_mov_b32_e32 v41, v2
	v_mov_b32_e32 v46, v2
	v_mov_b32_e32 v47, v2
	v_mov_b32_e32 v48, v2
	v_mov_b32_e32 v49, v2
	v_mov_b32_e32 v54, v2
	v_mov_b32_e32 v55, v2
	v_mov_b32_e32 v56, v2
	v_mov_b32_e32 v57, v2
	v_mov_b32_e32 v10, v2
	v_mov_b32_e32 v11, v2
	v_mov_b32_e32 v12, v2
	v_mov_b32_e32 v13, v2
	v_mov_b32_e32 v18, v2
	v_mov_b32_e32 v19, v2
	v_mov_b32_e32 v20, v2
	v_mov_b32_e32 v21, v2
	v_mov_b32_e32 v26, v2
	v_mov_b32_e32 v27, v2
	v_mov_b32_e32 v28, v2
	v_mov_b32_e32 v29, v2
	v_mov_b32_e32 v34, v2
	v_mov_b32_e32 v35, v2
	v_mov_b32_e32 v36, v2
	v_mov_b32_e32 v37, v2
	v_mov_b32_e32 v42, v2
	v_mov_b32_e32 v43, v2
	v_mov_b32_e32 v44, v2
	v_mov_b32_e32 v45, v2
	v_mov_b32_e32 v50, v2
	v_mov_b32_e32 v51, v2
	v_mov_b32_e32 v52, v2
	v_mov_b32_e32 v53, v2
	v_mov_b32_e32 v58, v2
	v_mov_b32_e32 v59, v2
	v_mov_b32_e32 v60, v2
	v_mov_b32_e32 v61, v2
	v_mov_b32_e32 v62, v2
	v_mov_b32_e32 v63, v2
	v_mov_b32_e32 v64, v2
	v_mov_b32_e32 v65, v2
	v_mov_b32_e32 v66, v2
	v_mov_b32_e32 v67, v2
	v_mov_b32_e32 v68, v2
	v_mov_b32_e32 v69, v2
	v_mov_b32_e32 v70, v2
	v_mov_b32_e32 v71, v2
	v_mov_b32_e32 v72, v2
	v_mov_b32_e32 v73, v2
	v_mov_b32_e32 v78, v2
	v_mov_b32_e32 v79, v2
	v_mov_b32_e32 v80, v2
	v_mov_b32_e32 v81, v2
	v_mov_b32_e32 v86, v2
	v_mov_b32_e32 v87, v2
	v_mov_b32_e32 v88, v2
	v_mov_b32_e32 v89, v2
	v_mov_b32_e32 v94, v2
	v_mov_b32_e32 v95, v2
	v_mov_b32_e32 v96, v2
	v_mov_b32_e32 v97, v2
	v_mov_b32_e32 v102, v2
	v_mov_b32_e32 v103, v2
	v_mov_b32_e32 v104, v2
	v_mov_b32_e32 v105, v2
	v_mov_b32_e32 v110, v2
	v_mov_b32_e32 v111, v2
	v_mov_b32_e32 v112, v2
	v_mov_b32_e32 v113, v2
	v_mov_b32_e32 v118, v2
	v_mov_b32_e32 v119, v2
	v_mov_b32_e32 v120, v2
	v_mov_b32_e32 v121, v2
	v_mov_b32_e32 v74, v2
	v_mov_b32_e32 v75, v2
	v_mov_b32_e32 v76, v2
	v_mov_b32_e32 v77, v2
	v_mov_b32_e32 v82, v2
	v_mov_b32_e32 v83, v2
	v_mov_b32_e32 v84, v2
	v_mov_b32_e32 v85, v2
	v_mov_b32_e32 v90, v2
	v_mov_b32_e32 v91, v2
	v_mov_b32_e32 v92, v2
	v_mov_b32_e32 v93, v2
	v_mov_b32_e32 v98, v2
	v_mov_b32_e32 v99, v2
	v_mov_b32_e32 v100, v2
	v_mov_b32_e32 v101, v2
	v_mov_b32_e32 v106, v2
	v_mov_b32_e32 v107, v2
	v_mov_b32_e32 v108, v2
	v_mov_b32_e32 v109, v2
	v_mov_b32_e32 v114, v2
	v_mov_b32_e32 v115, v2
	v_mov_b32_e32 v116, v2
	v_mov_b32_e32 v117, v2
	v_mov_b32_e32 v122, v2
	v_mov_b32_e32 v123, v2
	v_mov_b32_e32 v124, v2
	v_mov_b32_e32 v125, v2
	v_mov_b32_e32 v126, v2
	v_mov_b32_e32 v127, v2
	v_mov_b32_e32 v128, v2
	v_mov_b32_e32 v129, v2
	v_add_u32_e32 v253, 0x10000, v139
.LBB0_361:
	s_add_u32 s37, s24, s36
	s_addc_u32 s44, s25, 0
	s_add_u32 s42, s37, 0x100
	s_addc_u32 s43, s44, 0
	s_and_b64 s[38:39], s[30:31], exec
	s_cselect_b32 s39, s11, s43
	s_cselect_b32 s38, s40, s42
	s_add_u32 s36, s22, s36
	s_addc_u32 s42, s23, 0
	s_add_u32 s36, s36, 0x100
	s_addc_u32 s42, s42, 0
	s_add_i32 s64, 0, 0x10000
	s_and_b64 s[30:31], s[30:31], exec
	s_cselect_b32 s43, s9, s42
	s_cselect_b32 s42, s41, s36
	s_add_i32 s31, 0, 0x14000
	s_add_u32 s52, s37, 0x10080
	s_addc_u32 s53, s44, 0
	s_add_i32 s63, s64, s19
	s_add_i32 m0, s21, 0xc000
	s_add_i32 s66, s21, 0xe000
	s_add_i32 s60, s63, 0x2000
	s_add_u32 s50, s42, 0x10000
	ds_read_b128 v[144:147], v253
	ds_read_b128 v[148:151], v253 offset:1024
	ds_read_b128 v[152:155], v253 offset:2048
	ds_read_b128 v[156:159], v253 offset:3072
	s_addc_u32 s51, s43, 0
	s_add_i32 s62, s31, s19
	ds_read_b128 v[160:163], v253 offset:16384
	ds_read_b128 v[164:167], v253 offset:17408
	ds_read_b128 v[168:171], v253 offset:18432
	ds_read_b128 v[172:175], v253 offset:19456
	s_add_i32 s61, s62, 0x2000
	s_add_i32 s59, 0, 0x18000
	s_add_i32 s58, 0, 0x1c000
	s_add_u32 s36, s38, 0x10000
	s_addc_u32 s37, s39, 0
	s_add_i32 s45, s59, s19
	s_add_i32 s44, s45, 0x2000
	s_add_u32 s30, s42, 0x10080
	s_addc_u32 s31, s43, 0
	s_add_i32 s65, s58, s19
	s_add_i32 s64, s65, 0x2000
	ds_read_b128 v[176:179], v141
	ds_read_b128 v[180:183], v141 offset:1024
	ds_read_b128 v[184:187], v141 offset:2048
	ds_read_b128 v[188:191], v141 offset:3072
	ds_read_b128 v[204:207], v141 offset:4096
	ds_read_b128 v[208:211], v141 offset:5120
	ds_read_b128 v[212:215], v141 offset:6144
	ds_read_b128 v[216:219], v141 offset:7168
	global_load_lds_dwordx4 v134, s[52:53]
	s_mov_b32 m0, s66
	s_nop 0
	global_load_lds_dwordx4 v132, s[52:53]
	s_waitcnt vmcnt(8)
	s_waitcnt lgkmcnt(0)
	s_barrier
	s_setprio 1
	s_waitcnt lgkmcnt(0)
	v_mfma_f32_16x16x32_bf16 v[126:129], v[144:147], v[176:179], v[126:129]
	v_mfma_f32_16x16x32_bf16 v[122:125], v[152:155], v[176:179], v[122:125]
	v_mfma_f32_16x16x32_bf16 v[114:117], v[144:147], v[184:187], v[114:117]
	v_mfma_f32_16x16x32_bf16 v[106:109], v[152:155], v[184:187], v[106:109]
	v_mfma_f32_16x16x32_bf16 v[98:101], v[144:147], v[204:207], v[98:101]
	v_mfma_f32_16x16x32_bf16 v[90:93], v[152:155], v[204:207], v[90:93]
	v_mfma_f32_16x16x32_bf16 v[82:85], v[144:147], v[212:215], v[82:85]
	v_mfma_f32_16x16x32_bf16 v[74:77], v[152:155], v[212:215], v[74:77]
	v_mfma_f32_16x16x32_bf16 v[126:129], v[148:151], v[180:183], v[126:129]
	v_mfma_f32_16x16x32_bf16 v[122:125], v[156:159], v[180:183], v[122:125]
	v_mfma_f32_16x16x32_bf16 v[114:117], v[148:151], v[188:191], v[114:117]
	v_mfma_f32_16x16x32_bf16 v[106:109], v[156:159], v[188:191], v[106:109]
	v_mfma_f32_16x16x32_bf16 v[98:101], v[148:151], v[208:211], v[98:101]
	v_mfma_f32_16x16x32_bf16 v[90:93], v[156:159], v[208:211], v[90:93]
	v_mfma_f32_16x16x32_bf16 v[82:85], v[148:151], v[216:219], v[82:85]
	v_mfma_f32_16x16x32_bf16 v[74:77], v[156:159], v[216:219], v[74:77]
	s_setprio 0
	s_setprio 1
	v_mfma_f32_16x16x32_bf16 v[118:121], v[160:163], v[176:179], v[118:121]
	v_mfma_f32_16x16x32_bf16 v[110:113], v[168:171], v[176:179], v[110:113]
	v_mfma_f32_16x16x32_bf16 v[102:105], v[160:163], v[184:187], v[102:105]
	v_mfma_f32_16x16x32_bf16 v[94:97], v[168:171], v[184:187], v[94:97]
	v_mfma_f32_16x16x32_bf16 v[86:89], v[160:163], v[204:207], v[86:89]
	v_mfma_f32_16x16x32_bf16 v[78:81], v[168:171], v[204:207], v[78:81]
	v_mfma_f32_16x16x32_bf16 v[70:73], v[160:163], v[212:215], v[70:73]
	v_mfma_f32_16x16x32_bf16 v[66:69], v[168:171], v[212:215], v[66:69]
	v_mfma_f32_16x16x32_bf16 v[118:121], v[164:167], v[180:183], v[118:121]
	v_mfma_f32_16x16x32_bf16 v[110:113], v[172:175], v[180:183], v[110:113]
	v_mfma_f32_16x16x32_bf16 v[102:105], v[164:167], v[188:191], v[102:105]
	v_mfma_f32_16x16x32_bf16 v[94:97], v[172:175], v[188:191], v[94:97]
	v_mfma_f32_16x16x32_bf16 v[86:89], v[164:167], v[208:211], v[86:89]
	v_mfma_f32_16x16x32_bf16 v[78:81], v[172:175], v[208:211], v[78:81]
	v_mfma_f32_16x16x32_bf16 v[70:73], v[164:167], v[216:219], v[70:73]
	v_mfma_f32_16x16x32_bf16 v[66:69], v[172:175], v[216:219], v[66:69]
	s_setprio 0
	s_barrier
	s_mov_b32 m0, s63
	ds_read_b128 v[176:179], v141 offset:16384
	ds_read_b128 v[180:183], v141 offset:17408
	ds_read_b128 v[184:187], v141 offset:18432
	ds_read_b128 v[188:191], v141 offset:19456
	ds_read_b128 v[204:207], v141 offset:20480
	ds_read_b128 v[208:211], v141 offset:21504
	ds_read_b128 v[212:215], v141 offset:22528
	ds_read_b128 v[216:219], v141 offset:23552
	global_load_lds_dwordx4 v0, s[42:43]
	s_mov_b32 m0, s60
	s_nop 0
	global_load_lds_dwordx4 v130, s[42:43]
	s_mov_b32 m0, s62
	s_nop 0
	global_load_lds_dwordx4 v0, s[50:51]
	s_mov_b32 m0, s61
	s_nop 0
	global_load_lds_dwordx4 v130, s[50:51]
	s_mov_b32 m0, s21
	s_nop 0
	global_load_lds_dwordx4 v134, s[38:39]
	s_mov_b32 m0, s35
	s_nop 0
	global_load_lds_dwordx4 v132, s[38:39]
	s_waitcnt vmcnt(8)
	s_waitcnt lgkmcnt(0)
	s_barrier
	s_setprio 1
	s_waitcnt lgkmcnt(0)
	v_mfma_f32_16x16x32_bf16 v[62:65], v[144:147], v[176:179], v[62:65]
	v_mfma_f32_16x16x32_bf16 v[58:61], v[152:155], v[176:179], v[58:61]
	v_mfma_f32_16x16x32_bf16 v[50:53], v[144:147], v[184:187], v[50:53]
	v_mfma_f32_16x16x32_bf16 v[42:45], v[152:155], v[184:187], v[42:45]
	v_mfma_f32_16x16x32_bf16 v[34:37], v[144:147], v[204:207], v[34:37]
	v_mfma_f32_16x16x32_bf16 v[26:29], v[152:155], v[204:207], v[26:29]
	v_mfma_f32_16x16x32_bf16 v[18:21], v[144:147], v[212:215], v[18:21]
	v_mfma_f32_16x16x32_bf16 v[10:13], v[152:155], v[212:215], v[10:13]
	v_mfma_f32_16x16x32_bf16 v[62:65], v[148:151], v[180:183], v[62:65]
	v_mfma_f32_16x16x32_bf16 v[58:61], v[156:159], v[180:183], v[58:61]
	v_mfma_f32_16x16x32_bf16 v[50:53], v[148:151], v[188:191], v[50:53]
	v_mfma_f32_16x16x32_bf16 v[42:45], v[156:159], v[188:191], v[42:45]
	v_mfma_f32_16x16x32_bf16 v[34:37], v[148:151], v[208:211], v[34:37]
	v_mfma_f32_16x16x32_bf16 v[26:29], v[156:159], v[208:211], v[26:29]
	v_mfma_f32_16x16x32_bf16 v[18:21], v[148:151], v[216:219], v[18:21]
	v_mfma_f32_16x16x32_bf16 v[10:13], v[156:159], v[216:219], v[10:13]
	s_setprio 0
	s_setprio 1
	v_mfma_f32_16x16x32_bf16 v[54:57], v[160:163], v[176:179], v[54:57]
	v_mfma_f32_16x16x32_bf16 v[46:49], v[168:171], v[176:179], v[46:49]
	v_mfma_f32_16x16x32_bf16 v[38:41], v[160:163], v[184:187], v[38:41]
	v_mfma_f32_16x16x32_bf16 v[30:33], v[168:171], v[184:187], v[30:33]
	v_mfma_f32_16x16x32_bf16 v[22:25], v[160:163], v[204:207], v[22:25]
	v_mfma_f32_16x16x32_bf16 v[14:17], v[168:171], v[204:207], v[14:17]
	v_mfma_f32_16x16x32_bf16 v[6:9], v[160:163], v[212:215], v[6:9]
	v_mfma_f32_16x16x32_bf16 v[2:5], v[168:171], v[212:215], v[2:5]
	v_mfma_f32_16x16x32_bf16 v[54:57], v[164:167], v[180:183], v[54:57]
	v_mfma_f32_16x16x32_bf16 v[46:49], v[172:175], v[180:183], v[46:49]
	v_mfma_f32_16x16x32_bf16 v[38:41], v[164:167], v[188:191], v[38:41]
	v_mfma_f32_16x16x32_bf16 v[30:33], v[172:175], v[188:191], v[30:33]
	v_mfma_f32_16x16x32_bf16 v[22:25], v[164:167], v[208:211], v[22:25]
	v_mfma_f32_16x16x32_bf16 v[14:17], v[172:175], v[208:211], v[14:17]
	v_mfma_f32_16x16x32_bf16 v[6:9], v[164:167], v[216:219], v[6:9]
	v_mfma_f32_16x16x32_bf16 v[2:5], v[172:175], v[216:219], v[2:5]
	s_setprio 0
	s_barrier
	ds_read_b128 v[144:147], v253 offset:32768
	ds_read_b128 v[148:151], v253 offset:33792
	ds_read_b128 v[152:155], v253 offset:34816
	ds_read_b128 v[156:159], v253 offset:35840
	ds_read_b128 v[160:163], v253 offset:49152
	ds_read_b128 v[164:167], v253 offset:50176
	ds_read_b128 v[168:171], v253 offset:51200
	ds_read_b128 v[172:175], v253 offset:52224
	s_mov_b32 m0, s46
	ds_read_b128 v[176:179], v141 offset:32768
	ds_read_b128 v[180:183], v141 offset:33792
	ds_read_b128 v[184:187], v141 offset:34816
	ds_read_b128 v[188:191], v141 offset:35840
	ds_read_b128 v[204:207], v141 offset:36864
	ds_read_b128 v[208:211], v141 offset:37888
	ds_read_b128 v[212:215], v141 offset:38912
	ds_read_b128 v[216:219], v141 offset:39936
	global_load_lds_dwordx4 v134, s[36:37]
	s_mov_b32 m0, s54
	s_nop 0
	global_load_lds_dwordx4 v132, s[36:37]
	s_waitcnt vmcnt(8)
	s_waitcnt lgkmcnt(0)
	s_barrier
	s_setprio 1
	s_waitcnt lgkmcnt(0)
	v_mfma_f32_16x16x32_bf16 v[126:129], v[144:147], v[176:179], v[126:129]
	v_mfma_f32_16x16x32_bf16 v[122:125], v[152:155], v[176:179], v[122:125]
	v_mfma_f32_16x16x32_bf16 v[114:117], v[144:147], v[184:187], v[114:117]
	v_mfma_f32_16x16x32_bf16 v[106:109], v[152:155], v[184:187], v[106:109]
	v_mfma_f32_16x16x32_bf16 v[98:101], v[144:147], v[204:207], v[98:101]
	v_mfma_f32_16x16x32_bf16 v[90:93], v[152:155], v[204:207], v[90:93]
	v_mfma_f32_16x16x32_bf16 v[82:85], v[144:147], v[212:215], v[82:85]
	v_mfma_f32_16x16x32_bf16 v[74:77], v[152:155], v[212:215], v[74:77]
	v_mfma_f32_16x16x32_bf16 v[126:129], v[148:151], v[180:183], v[126:129]
	v_mfma_f32_16x16x32_bf16 v[122:125], v[156:159], v[180:183], v[122:125]
	v_mfma_f32_16x16x32_bf16 v[114:117], v[148:151], v[188:191], v[114:117]
	v_mfma_f32_16x16x32_bf16 v[106:109], v[156:159], v[188:191], v[106:109]
	v_mfma_f32_16x16x32_bf16 v[98:101], v[148:151], v[208:211], v[98:101]
	v_mfma_f32_16x16x32_bf16 v[90:93], v[156:159], v[208:211], v[90:93]
	v_mfma_f32_16x16x32_bf16 v[82:85], v[148:151], v[216:219], v[82:85]
	v_mfma_f32_16x16x32_bf16 v[74:77], v[156:159], v[216:219], v[74:77]
	s_setprio 0
	s_setprio 1
	v_mfma_f32_16x16x32_bf16 v[118:121], v[160:163], v[176:179], v[118:121]
	v_mfma_f32_16x16x32_bf16 v[110:113], v[168:171], v[176:179], v[110:113]
	v_mfma_f32_16x16x32_bf16 v[102:105], v[160:163], v[184:187], v[102:105]
	v_mfma_f32_16x16x32_bf16 v[94:97], v[168:171], v[184:187], v[94:97]
	v_mfma_f32_16x16x32_bf16 v[86:89], v[160:163], v[204:207], v[86:89]
	v_mfma_f32_16x16x32_bf16 v[78:81], v[168:171], v[204:207], v[78:81]
	v_mfma_f32_16x16x32_bf16 v[70:73], v[160:163], v[212:215], v[70:73]
	v_mfma_f32_16x16x32_bf16 v[66:69], v[168:171], v[212:215], v[66:69]
	v_mfma_f32_16x16x32_bf16 v[118:121], v[164:167], v[180:183], v[118:121]
	v_mfma_f32_16x16x32_bf16 v[110:113], v[172:175], v[180:183], v[110:113]
	v_mfma_f32_16x16x32_bf16 v[102:105], v[164:167], v[188:191], v[102:105]
	v_mfma_f32_16x16x32_bf16 v[94:97], v[172:175], v[188:191], v[94:97]
	v_mfma_f32_16x16x32_bf16 v[86:89], v[164:167], v[208:211], v[86:89]
	v_mfma_f32_16x16x32_bf16 v[78:81], v[172:175], v[208:211], v[78:81]
	v_mfma_f32_16x16x32_bf16 v[70:73], v[164:167], v[216:219], v[70:73]
	v_mfma_f32_16x16x32_bf16 v[66:69], v[172:175], v[216:219], v[66:69]
	s_setprio 0
	s_barrier
	s_add_u32 s100, s38, 0x80
	s_addc_u32 s101, s39, 0
	s_add_u32 s98, s42, 0x80
	s_addc_u32 s99, s43, 0
	s_mov_b32 m0, s45
	ds_read_b128 v[176:179], v141 offset:49152
	ds_read_b128 v[180:183], v141 offset:50176
	ds_read_b128 v[184:187], v141 offset:51200
	ds_read_b128 v[188:191], v141 offset:52224
	ds_read_b128 v[204:207], v141 offset:53248
	ds_read_b128 v[208:211], v141 offset:54272
	ds_read_b128 v[212:215], v141 offset:55296
	ds_read_b128 v[216:219], v141 offset:56320
	global_load_lds_dwordx4 v0, s[98:99]
	s_mov_b32 m0, s44
	s_nop 0
	global_load_lds_dwordx4 v130, s[98:99]
	s_mov_b32 m0, s65
	s_nop 0
	global_load_lds_dwordx4 v0, s[30:31]
	s_mov_b32 m0, s64
	s_nop 0
	global_load_lds_dwordx4 v130, s[30:31]
	s_mov_b32 m0, s55
	s_nop 0
	global_load_lds_dwordx4 v134, s[100:101]
	s_mov_b32 m0, s56
	s_nop 0
	global_load_lds_dwordx4 v132, s[100:101]
	s_waitcnt vmcnt(8)
	s_waitcnt lgkmcnt(0)
	s_barrier
	s_setprio 1
	s_waitcnt lgkmcnt(0)
	v_mfma_f32_16x16x32_bf16 v[62:65], v[144:147], v[176:179], v[62:65]
	v_mfma_f32_16x16x32_bf16 v[58:61], v[152:155], v[176:179], v[58:61]
	v_mfma_f32_16x16x32_bf16 v[50:53], v[144:147], v[184:187], v[50:53]
	v_mfma_f32_16x16x32_bf16 v[42:45], v[152:155], v[184:187], v[42:45]
	v_mfma_f32_16x16x32_bf16 v[34:37], v[144:147], v[204:207], v[34:37]
	v_mfma_f32_16x16x32_bf16 v[26:29], v[152:155], v[204:207], v[26:29]
	v_mfma_f32_16x16x32_bf16 v[18:21], v[144:147], v[212:215], v[18:21]
	v_mfma_f32_16x16x32_bf16 v[10:13], v[152:155], v[212:215], v[10:13]
	v_mfma_f32_16x16x32_bf16 v[62:65], v[148:151], v[180:183], v[62:65]
	v_mfma_f32_16x16x32_bf16 v[58:61], v[156:159], v[180:183], v[58:61]
	v_mfma_f32_16x16x32_bf16 v[50:53], v[148:151], v[188:191], v[50:53]
	v_mfma_f32_16x16x32_bf16 v[42:45], v[156:159], v[188:191], v[42:45]
	v_mfma_f32_16x16x32_bf16 v[34:37], v[148:151], v[208:211], v[34:37]
	v_mfma_f32_16x16x32_bf16 v[26:29], v[156:159], v[208:211], v[26:29]
	v_mfma_f32_16x16x32_bf16 v[18:21], v[148:151], v[216:219], v[18:21]
	v_mfma_f32_16x16x32_bf16 v[10:13], v[156:159], v[216:219], v[10:13]
	s_setprio 0
	s_setprio 1
	v_mfma_f32_16x16x32_bf16 v[54:57], v[160:163], v[176:179], v[54:57]
	v_mfma_f32_16x16x32_bf16 v[46:49], v[168:171], v[176:179], v[46:49]
	v_mfma_f32_16x16x32_bf16 v[38:41], v[160:163], v[184:187], v[38:41]
	v_mfma_f32_16x16x32_bf16 v[30:33], v[168:171], v[184:187], v[30:33]
	v_mfma_f32_16x16x32_bf16 v[22:25], v[160:163], v[204:207], v[22:25]
	v_mfma_f32_16x16x32_bf16 v[14:17], v[168:171], v[204:207], v[14:17]
	v_mfma_f32_16x16x32_bf16 v[6:9], v[160:163], v[212:215], v[6:9]
	v_mfma_f32_16x16x32_bf16 v[2:5], v[168:171], v[212:215], v[2:5]
	v_mfma_f32_16x16x32_bf16 v[54:57], v[164:167], v[180:183], v[54:57]
	v_mfma_f32_16x16x32_bf16 v[46:49], v[172:175], v[180:183], v[46:49]
	v_mfma_f32_16x16x32_bf16 v[38:41], v[164:167], v[188:191], v[38:41]
	v_mfma_f32_16x16x32_bf16 v[30:33], v[172:175], v[188:191], v[30:33]
	v_mfma_f32_16x16x32_bf16 v[22:25], v[164:167], v[208:211], v[22:25]
	v_mfma_f32_16x16x32_bf16 v[14:17], v[172:175], v[208:211], v[14:17]
	v_mfma_f32_16x16x32_bf16 v[6:9], v[164:167], v[216:219], v[6:9]
	v_mfma_f32_16x16x32_bf16 v[2:5], v[172:175], v[216:219], v[2:5]
	s_setprio 0
	s_barrier
	s_movk_i32 s36, 0x100
	s_andn2_b64 vcc, exec, s[26:27]
	s_mov_b64 s[30:31], -1
	s_mov_b64 s[26:27], 0
	s_cbranch_vccz .LBB0_361
	s_and_b64 vcc, exec, s[6:7]
	s_cbranch_vccz .LBB0_364
	s_barrier

.LBB0_976:
	s_add_i32 s13, s27, -2
	s_add_u32 s38, s38, 0x80080
	s_addc_u32 s39, s39, 0
	s_add_u32 s15, s42, 0x100
	v_mov_b32_e32 v2, 0
	s_addc_u32 s21, s43, 0
	s_mov_b32 s33, 0
	v_mov_b32_e32 v3, v2
	v_mov_b32_e32 v4, v2
	v_mov_b32_e32 v5, v2
	v_mov_b32_e32 v6, v2
	v_mov_b32_e32 v7, v2
	v_mov_b32_e32 v8, v2
	v_mov_b32_e32 v9, v2
	v_mov_b32_e32 v14, v2
	v_mov_b32_e32 v15, v2
	v_mov_b32_e32 v16, v2
	v_mov_b32_e32 v17, v2
	v_mov_b32_e32 v22, v2
	v_mov_b32_e32 v23, v2
	v_mov_b32_e32 v24, v2
	v_mov_b32_e32 v25, v2
	v_mov_b32_e32 v30, v2
	v_mov_b32_e32 v31, v2
	v_mov_b32_e32 v32, v2
	v_mov_b32_e32 v33, v2
	v_mov_b32_e32 v38, v2
	v_mov_b32_e32 v39, v2
	v_mov_b32_e32 v40, v2
	v_mov_b32_e32 v41, v2
	v_mov_b32_e32 v46, v2
	v_mov_b32_e32 v47, v2
	v_mov_b32_e32 v48, v2
	v_mov_b32_e32 v49, v2
	v_mov_b32_e32 v54, v2
	v_mov_b32_e32 v55, v2
	v_mov_b32_e32 v56, v2
	v_mov_b32_e32 v57, v2
	v_mov_b32_e32 v10, v2
	v_mov_b32_e32 v11, v2
	v_mov_b32_e32 v12, v2
	v_mov_b32_e32 v13, v2
	v_mov_b32_e32 v18, v2
	v_mov_b32_e32 v19, v2
	v_mov_b32_e32 v20, v2
	v_mov_b32_e32 v21, v2
	v_mov_b32_e32 v26, v2
	v_mov_b32_e32 v27, v2
	v_mov_b32_e32 v28, v2
	v_mov_b32_e32 v29, v2
	v_mov_b32_e32 v34, v2
	v_mov_b32_e32 v35, v2
	v_mov_b32_e32 v36, v2
	v_mov_b32_e32 v37, v2
	v_mov_b32_e32 v42, v2
	v_mov_b32_e32 v43, v2
	v_mov_b32_e32 v44, v2
	v_mov_b32_e32 v45, v2
	v_mov_b32_e32 v50, v2
	v_mov_b32_e32 v51, v2
	v_mov_b32_e32 v52, v2
	v_mov_b32_e32 v53, v2
	v_mov_b32_e32 v58, v2
	v_mov_b32_e32 v59, v2
	v_mov_b32_e32 v60, v2
	v_mov_b32_e32 v61, v2
	v_mov_b32_e32 v62, v2
	v_mov_b32_e32 v63, v2
	v_mov_b32_e32 v64, v2
	v_mov_b32_e32 v65, v2
	v_mov_b32_e32 v66, v2
	v_mov_b32_e32 v67, v2
	v_mov_b32_e32 v68, v2
	v_mov_b32_e32 v69, v2
	v_mov_b32_e32 v70, v2
	v_mov_b32_e32 v71, v2
	v_mov_b32_e32 v72, v2
	v_mov_b32_e32 v73, v2
	v_mov_b32_e32 v78, v2
	v_mov_b32_e32 v79, v2
	v_mov_b32_e32 v80, v2
	v_mov_b32_e32 v81, v2
	v_mov_b32_e32 v86, v2
	v_mov_b32_e32 v87, v2
	v_mov_b32_e32 v88, v2
	v_mov_b32_e32 v89, v2
	v_mov_b32_e32 v94, v2
	v_mov_b32_e32 v95, v2
	v_mov_b32_e32 v96, v2
	v_mov_b32_e32 v97, v2
	v_mov_b32_e32 v102, v2
	v_mov_b32_e32 v103, v2
	v_mov_b32_e32 v104, v2
	v_mov_b32_e32 v105, v2
	v_mov_b32_e32 v106, v2
	v_mov_b32_e32 v107, v2
	v_mov_b32_e32 v108, v2
	v_mov_b32_e32 v109, v2
	v_mov_b32_e32 v114, v2
	v_mov_b32_e32 v115, v2
	v_mov_b32_e32 v116, v2
	v_mov_b32_e32 v117, v2
	v_mov_b32_e32 v74, v2
	v_mov_b32_e32 v75, v2
	v_mov_b32_e32 v76, v2
	v_mov_b32_e32 v77, v2
	v_mov_b32_e32 v82, v2
	v_mov_b32_e32 v83, v2
	v_mov_b32_e32 v84, v2
	v_mov_b32_e32 v85, v2
	v_mov_b32_e32 v90, v2
	v_mov_b32_e32 v91, v2
	v_mov_b32_e32 v92, v2
	v_mov_b32_e32 v93, v2
	v_mov_b32_e32 v98, v2
	v_mov_b32_e32 v99, v2
	v_mov_b32_e32 v100, v2
	v_mov_b32_e32 v101, v2
	v_mov_b32_e32 v110, v2
	v_mov_b32_e32 v111, v2
	v_mov_b32_e32 v112, v2
	v_mov_b32_e32 v113, v2
	v_mov_b32_e32 v118, v2
	v_mov_b32_e32 v119, v2
	v_mov_b32_e32 v120, v2
	v_mov_b32_e32 v121, v2
	v_mov_b32_e32 v138, v2
	v_mov_b32_e32 v139, v2
	v_mov_b32_e32 v140, v2
	v_mov_b32_e32 v141, v2
	v_mov_b32_e32 v142, v2
	v_mov_b32_e32 v143, v2
	v_mov_b32_e32 v144, v2
	v_mov_b32_e32 v145, v2
	s_waitcnt vmcnt(0)
	v_add_u32_e32 v253, 0x10000, v192
.LBB0_977:
	s_add_i32 s37, s33, 2
	s_add_u32 s40, s38, 0xfff80080
	s_addc_u32 s41, s39, -1
	s_add_i32 s44, 0, 0x10000
	s_cmp_eq_u32 s13, s33
	s_cselect_b32 s51, s23, s41
	s_cselect_b32 s50, s22, s40
	s_cselect_b32 s43, s25, s21
	s_cselect_b32 s42, s24, s15
	s_add_i32 s33, 0, 0x14000
	ds_read_b128 v[122:125], v253
	ds_read_b128 v[126:129], v253 offset:1024
	ds_read_b128 v[130:133], v253 offset:2048
	ds_read_b128 v[134:137], v253 offset:3072
	ds_read_b128 v[146:149], v253 offset:16384
	ds_read_b128 v[150:153], v253 offset:17408
	ds_read_b128 v[154:157], v253 offset:18432
	ds_read_b128 v[158:161], v253 offset:19456
	s_add_i32 m0, s31, 0xc000
	ds_read_b128 v[162:165], v204
	ds_read_b128 v[176:179], v204 offset:1024
	ds_read_b128 v[180:183], v204 offset:2048
	ds_read_b128 v[184:187], v204 offset:3072
	ds_read_b128 v[206:209], v204 offset:4096
	ds_read_b128 v[210:213], v204 offset:5120
	ds_read_b128 v[214:217], v204 offset:6144
	ds_read_b128 v[218:221], v204 offset:7168
	global_load_lds_dwordx4 v172, s[38:39]
	s_add_i32 m0, s31, 0xe000
	s_nop 0
	global_load_lds_dwordx4 v174, s[38:39]
	s_waitcnt vmcnt(8)
	s_waitcnt lgkmcnt(0)
	s_barrier
	s_setprio 1
	s_waitcnt lgkmcnt(0)
	v_mfma_f32_16x16x32_bf16 v[142:145], v[122:125], v[162:165], v[142:145]
	v_mfma_f32_16x16x32_bf16 v[138:141], v[130:133], v[162:165], v[138:141]
	v_mfma_f32_16x16x32_bf16 v[118:121], v[122:125], v[180:183], v[118:121]
	v_mfma_f32_16x16x32_bf16 v[110:113], v[130:133], v[180:183], v[110:113]
	v_mfma_f32_16x16x32_bf16 v[98:101], v[122:125], v[206:209], v[98:101]
	v_mfma_f32_16x16x32_bf16 v[90:93], v[130:133], v[206:209], v[90:93]
	v_mfma_f32_16x16x32_bf16 v[82:85], v[122:125], v[214:217], v[82:85]
	v_mfma_f32_16x16x32_bf16 v[74:77], v[130:133], v[214:217], v[74:77]
	v_mfma_f32_16x16x32_bf16 v[142:145], v[126:129], v[176:179], v[142:145]
	v_mfma_f32_16x16x32_bf16 v[138:141], v[134:137], v[176:179], v[138:141]
	v_mfma_f32_16x16x32_bf16 v[118:121], v[126:129], v[184:187], v[118:121]
	v_mfma_f32_16x16x32_bf16 v[110:113], v[134:137], v[184:187], v[110:113]
	v_mfma_f32_16x16x32_bf16 v[98:101], v[126:129], v[210:213], v[98:101]
	v_mfma_f32_16x16x32_bf16 v[90:93], v[134:137], v[210:213], v[90:93]
	v_mfma_f32_16x16x32_bf16 v[82:85], v[126:129], v[218:221], v[82:85]
	v_mfma_f32_16x16x32_bf16 v[74:77], v[134:137], v[218:221], v[74:77]
	s_setprio 0
	s_setprio 1
	v_mfma_f32_16x16x32_bf16 v[114:117], v[146:149], v[162:165], v[114:117]
	v_mfma_f32_16x16x32_bf16 v[106:109], v[154:157], v[162:165], v[106:109]
	v_mfma_f32_16x16x32_bf16 v[102:105], v[146:149], v[180:183], v[102:105]
	v_mfma_f32_16x16x32_bf16 v[94:97], v[154:157], v[180:183], v[94:97]
	v_mfma_f32_16x16x32_bf16 v[86:89], v[146:149], v[206:209], v[86:89]
	v_mfma_f32_16x16x32_bf16 v[78:81], v[154:157], v[206:209], v[78:81]
	v_mfma_f32_16x16x32_bf16 v[70:73], v[146:149], v[214:217], v[70:73]
	v_mfma_f32_16x16x32_bf16 v[66:69], v[154:157], v[214:217], v[66:69]
	v_mfma_f32_16x16x32_bf16 v[114:117], v[150:153], v[176:179], v[114:117]
	v_mfma_f32_16x16x32_bf16 v[106:109], v[158:161], v[176:179], v[106:109]
	v_mfma_f32_16x16x32_bf16 v[102:105], v[150:153], v[184:187], v[102:105]
	v_mfma_f32_16x16x32_bf16 v[94:97], v[158:161], v[184:187], v[94:97]
	v_mfma_f32_16x16x32_bf16 v[86:89], v[150:153], v[210:213], v[86:89]
	v_mfma_f32_16x16x32_bf16 v[78:81], v[158:161], v[210:213], v[78:81]
	v_mfma_f32_16x16x32_bf16 v[70:73], v[150:153], v[218:221], v[70:73]
	v_mfma_f32_16x16x32_bf16 v[66:69], v[158:161], v[218:221], v[66:69]
	s_setprio 0
	s_barrier
	s_add_i32 s40, s44, s19
	s_mov_b32 m0, s40
	ds_read_b128 v[162:165], v204 offset:16384
	ds_read_b128 v[176:179], v204 offset:17408
	ds_read_b128 v[180:183], v204 offset:18432
	ds_read_b128 v[184:187], v204 offset:19456
	ds_read_b128 v[206:209], v204 offset:20480
	ds_read_b128 v[210:213], v204 offset:21504
	ds_read_b128 v[214:217], v204 offset:22528
	ds_read_b128 v[218:221], v204 offset:23552
	global_load_lds_dwordx4 v0, s[42:43]
	s_add_i32 m0, s40, 0x2000
	s_add_u32 s40, s42, 0x80000
	s_addc_u32 s41, s43, 0
	s_add_i32 s33, s33, s19
	global_load_lds_dwordx4 v170, s[42:43]
	s_mov_b32 m0, s33
	s_nop 0
	global_load_lds_dwordx4 v0, s[40:41]
	s_add_i32 m0, s33, 0x2000
	s_nop 0
	global_load_lds_dwordx4 v170, s[40:41]
	s_mov_b32 m0, s31
	s_nop 0
	global_load_lds_dwordx4 v166, s[50:51]
	s_mov_b32 m0, s34
	s_nop 0
	global_load_lds_dwordx4 v168, s[50:51]
	s_waitcnt vmcnt(8)
	s_waitcnt lgkmcnt(0)
	s_barrier
	s_setprio 1
	s_waitcnt lgkmcnt(0)
	v_mfma_f32_16x16x32_bf16 v[62:65], v[122:125], v[162:165], v[62:65]
	v_mfma_f32_16x16x32_bf16 v[58:61], v[130:133], v[162:165], v[58:61]
	v_mfma_f32_16x16x32_bf16 v[50:53], v[122:125], v[180:183], v[50:53]
	v_mfma_f32_16x16x32_bf16 v[42:45], v[130:133], v[180:183], v[42:45]
	v_mfma_f32_16x16x32_bf16 v[34:37], v[122:125], v[206:209], v[34:37]
	v_mfma_f32_16x16x32_bf16 v[26:29], v[130:133], v[206:209], v[26:29]
	v_mfma_f32_16x16x32_bf16 v[18:21], v[122:125], v[214:217], v[18:21]
	v_mfma_f32_16x16x32_bf16 v[10:13], v[130:133], v[214:217], v[10:13]
	v_mfma_f32_16x16x32_bf16 v[62:65], v[126:129], v[176:179], v[62:65]
	v_mfma_f32_16x16x32_bf16 v[58:61], v[134:137], v[176:179], v[58:61]
	v_mfma_f32_16x16x32_bf16 v[50:53], v[126:129], v[184:187], v[50:53]
	v_mfma_f32_16x16x32_bf16 v[42:45], v[134:137], v[184:187], v[42:45]
	v_mfma_f32_16x16x32_bf16 v[34:37], v[126:129], v[210:213], v[34:37]
	v_mfma_f32_16x16x32_bf16 v[26:29], v[134:137], v[210:213], v[26:29]
	v_mfma_f32_16x16x32_bf16 v[18:21], v[126:129], v[218:221], v[18:21]
	v_mfma_f32_16x16x32_bf16 v[10:13], v[134:137], v[218:221], v[10:13]
	s_setprio 0
	s_setprio 1
	v_mfma_f32_16x16x32_bf16 v[54:57], v[146:149], v[162:165], v[54:57]
	v_mfma_f32_16x16x32_bf16 v[46:49], v[154:157], v[162:165], v[46:49]
	v_mfma_f32_16x16x32_bf16 v[38:41], v[146:149], v[180:183], v[38:41]
	v_mfma_f32_16x16x32_bf16 v[30:33], v[154:157], v[180:183], v[30:33]
	v_mfma_f32_16x16x32_bf16 v[22:25], v[146:149], v[206:209], v[22:25]
	v_mfma_f32_16x16x32_bf16 v[14:17], v[154:157], v[206:209], v[14:17]
	v_mfma_f32_16x16x32_bf16 v[6:9], v[146:149], v[214:217], v[6:9]
	v_mfma_f32_16x16x32_bf16 v[2:5], v[154:157], v[214:217], v[2:5]
	v_mfma_f32_16x16x32_bf16 v[54:57], v[150:153], v[176:179], v[54:57]
	v_mfma_f32_16x16x32_bf16 v[46:49], v[158:161], v[176:179], v[46:49]
	v_mfma_f32_16x16x32_bf16 v[38:41], v[150:153], v[184:187], v[38:41]
	v_mfma_f32_16x16x32_bf16 v[30:33], v[158:161], v[184:187], v[30:33]
	v_mfma_f32_16x16x32_bf16 v[22:25], v[150:153], v[210:213], v[22:25]
	v_mfma_f32_16x16x32_bf16 v[14:17], v[158:161], v[210:213], v[14:17]
	v_mfma_f32_16x16x32_bf16 v[6:9], v[150:153], v[218:221], v[6:9]
	v_mfma_f32_16x16x32_bf16 v[2:5], v[158:161], v[218:221], v[2:5]
	s_setprio 0
	s_barrier
	s_add_i32 s33, 0, 0x18000
	s_add_i32 s44, 0, 0x1c000
	ds_read_b128 v[122:125], v253 offset:32768
	ds_read_b128 v[126:129], v253 offset:33792
	ds_read_b128 v[130:133], v253 offset:34816
	ds_read_b128 v[134:137], v253 offset:35840
	ds_read_b128 v[146:149], v253 offset:49152
	ds_read_b128 v[150:153], v253 offset:50176
	ds_read_b128 v[154:157], v253 offset:51200
	ds_read_b128 v[158:161], v253 offset:52224
	s_add_u32 s40, s50, 0x80000
	s_addc_u32 s41, s51, 0
	s_mov_b32 m0, s35
	ds_read_b128 v[162:165], v204 offset:32768
	ds_read_b128 v[176:179], v204 offset:33792
	ds_read_b128 v[180:183], v204 offset:34816
	ds_read_b128 v[184:187], v204 offset:35840
	ds_read_b128 v[206:209], v204 offset:36864
	ds_read_b128 v[210:213], v204 offset:37888
	ds_read_b128 v[214:217], v204 offset:38912
	ds_read_b128 v[218:221], v204 offset:39936
	global_load_lds_dwordx4 v166, s[40:41]
	s_mov_b32 m0, s46
	s_nop 0
	global_load_lds_dwordx4 v168, s[40:41]
	s_waitcnt vmcnt(8)
	s_waitcnt lgkmcnt(0)
	s_barrier
	s_setprio 1
	s_waitcnt lgkmcnt(0)
	v_mfma_f32_16x16x32_bf16 v[142:145], v[122:125], v[162:165], v[142:145]
	v_mfma_f32_16x16x32_bf16 v[138:141], v[130:133], v[162:165], v[138:141]
	v_mfma_f32_16x16x32_bf16 v[118:121], v[122:125], v[180:183], v[118:121]
	v_mfma_f32_16x16x32_bf16 v[110:113], v[130:133], v[180:183], v[110:113]
	v_mfma_f32_16x16x32_bf16 v[98:101], v[122:125], v[206:209], v[98:101]
	v_mfma_f32_16x16x32_bf16 v[90:93], v[130:133], v[206:209], v[90:93]
	v_mfma_f32_16x16x32_bf16 v[82:85], v[122:125], v[214:217], v[82:85]
	v_mfma_f32_16x16x32_bf16 v[74:77], v[130:133], v[214:217], v[74:77]
	v_mfma_f32_16x16x32_bf16 v[142:145], v[126:129], v[176:179], v[142:145]
	v_mfma_f32_16x16x32_bf16 v[138:141], v[134:137], v[176:179], v[138:141]
	v_mfma_f32_16x16x32_bf16 v[118:121], v[126:129], v[184:187], v[118:121]
	v_mfma_f32_16x16x32_bf16 v[110:113], v[134:137], v[184:187], v[110:113]
	v_mfma_f32_16x16x32_bf16 v[98:101], v[126:129], v[210:213], v[98:101]
	v_mfma_f32_16x16x32_bf16 v[90:93], v[134:137], v[210:213], v[90:93]
	v_mfma_f32_16x16x32_bf16 v[82:85], v[126:129], v[218:221], v[82:85]
	v_mfma_f32_16x16x32_bf16 v[74:77], v[134:137], v[218:221], v[74:77]
	s_setprio 0
	s_setprio 1
	v_mfma_f32_16x16x32_bf16 v[114:117], v[146:149], v[162:165], v[114:117]
	v_mfma_f32_16x16x32_bf16 v[106:109], v[154:157], v[162:165], v[106:109]
	v_mfma_f32_16x16x32_bf16 v[102:105], v[146:149], v[180:183], v[102:105]
	v_mfma_f32_16x16x32_bf16 v[94:97], v[154:157], v[180:183], v[94:97]
	v_mfma_f32_16x16x32_bf16 v[86:89], v[146:149], v[206:209], v[86:89]
	v_mfma_f32_16x16x32_bf16 v[78:81], v[154:157], v[206:209], v[78:81]
	v_mfma_f32_16x16x32_bf16 v[70:73], v[146:149], v[214:217], v[70:73]
	v_mfma_f32_16x16x32_bf16 v[66:69], v[154:157], v[214:217], v[66:69]
	v_mfma_f32_16x16x32_bf16 v[114:117], v[150:153], v[176:179], v[114:117]
	v_mfma_f32_16x16x32_bf16 v[106:109], v[158:161], v[176:179], v[106:109]
	v_mfma_f32_16x16x32_bf16 v[102:105], v[150:153], v[184:187], v[102:105]
	v_mfma_f32_16x16x32_bf16 v[94:97], v[158:161], v[184:187], v[94:97]
	v_mfma_f32_16x16x32_bf16 v[86:89], v[150:153], v[210:213], v[86:89]
	v_mfma_f32_16x16x32_bf16 v[78:81], v[158:161], v[210:213], v[78:81]
	v_mfma_f32_16x16x32_bf16 v[70:73], v[150:153], v[218:221], v[70:73]
	v_mfma_f32_16x16x32_bf16 v[66:69], v[158:161], v[218:221], v[66:69]
	s_setprio 0
	s_barrier
	s_add_u32 s100, s40, 0xfff80080
	s_addc_u32 s101, s41, -1
	s_add_u32 s98, s42, 0x80
	s_addc_u32 s99, s43, 0
	s_add_i32 s33, s33, s19
	s_mov_b32 m0, s33
	ds_read_b128 v[162:165], v204 offset:49152
	ds_read_b128 v[176:179], v204 offset:50176
	ds_read_b128 v[180:183], v204 offset:51200
	ds_read_b128 v[184:187], v204 offset:52224
	ds_read_b128 v[206:209], v204 offset:53248
	ds_read_b128 v[210:213], v204 offset:54272
	ds_read_b128 v[214:217], v204 offset:55296
	ds_read_b128 v[218:221], v204 offset:56320
	global_load_lds_dwordx4 v0, s[98:99]
	s_add_i32 m0, s33, 0x2000
	s_add_u32 s40, s42, 0x80080
	s_addc_u32 s41, s43, 0
	s_add_i32 s33, s44, s19
	global_load_lds_dwordx4 v170, s[98:99]
	s_mov_b32 m0, s33
	s_nop 0
	global_load_lds_dwordx4 v0, s[40:41]
	s_add_i32 m0, s33, 0x2000
	s_nop 0
	global_load_lds_dwordx4 v170, s[40:41]
	s_mov_b32 m0, s54
	s_nop 0
	global_load_lds_dwordx4 v166, s[100:101]
	s_mov_b32 m0, s55
	s_nop 0
	global_load_lds_dwordx4 v168, s[100:101]
	s_waitcnt vmcnt(8)
	s_waitcnt lgkmcnt(0)
	s_barrier
	s_setprio 1
	s_waitcnt lgkmcnt(0)
	v_mfma_f32_16x16x32_bf16 v[62:65], v[122:125], v[162:165], v[62:65]
	v_mfma_f32_16x16x32_bf16 v[58:61], v[130:133], v[162:165], v[58:61]
	v_mfma_f32_16x16x32_bf16 v[50:53], v[122:125], v[180:183], v[50:53]
	v_mfma_f32_16x16x32_bf16 v[42:45], v[130:133], v[180:183], v[42:45]
	v_mfma_f32_16x16x32_bf16 v[34:37], v[122:125], v[206:209], v[34:37]
	v_mfma_f32_16x16x32_bf16 v[26:29], v[130:133], v[206:209], v[26:29]
	v_mfma_f32_16x16x32_bf16 v[18:21], v[122:125], v[214:217], v[18:21]
	v_mfma_f32_16x16x32_bf16 v[10:13], v[130:133], v[214:217], v[10:13]
	v_mfma_f32_16x16x32_bf16 v[62:65], v[126:129], v[176:179], v[62:65]
	v_mfma_f32_16x16x32_bf16 v[58:61], v[134:137], v[176:179], v[58:61]
	v_mfma_f32_16x16x32_bf16 v[50:53], v[126:129], v[184:187], v[50:53]
	v_mfma_f32_16x16x32_bf16 v[42:45], v[134:137], v[184:187], v[42:45]
	v_mfma_f32_16x16x32_bf16 v[34:37], v[126:129], v[210:213], v[34:37]
	v_mfma_f32_16x16x32_bf16 v[26:29], v[134:137], v[210:213], v[26:29]
	v_mfma_f32_16x16x32_bf16 v[18:21], v[126:129], v[218:221], v[18:21]
	v_mfma_f32_16x16x32_bf16 v[10:13], v[134:137], v[218:221], v[10:13]
	s_setprio 0
	s_setprio 1
	v_mfma_f32_16x16x32_bf16 v[54:57], v[146:149], v[162:165], v[54:57]
	v_mfma_f32_16x16x32_bf16 v[46:49], v[154:157], v[162:165], v[46:49]
	v_mfma_f32_16x16x32_bf16 v[38:41], v[146:149], v[180:183], v[38:41]
	v_mfma_f32_16x16x32_bf16 v[30:33], v[154:157], v[180:183], v[30:33]
	v_mfma_f32_16x16x32_bf16 v[22:25], v[146:149], v[206:209], v[22:25]
	v_mfma_f32_16x16x32_bf16 v[14:17], v[154:157], v[206:209], v[14:17]
	v_mfma_f32_16x16x32_bf16 v[6:9], v[146:149], v[214:217], v[6:9]
	v_mfma_f32_16x16x32_bf16 v[2:5], v[154:157], v[214:217], v[2:5]
	v_mfma_f32_16x16x32_bf16 v[54:57], v[150:153], v[176:179], v[54:57]
	v_mfma_f32_16x16x32_bf16 v[46:49], v[158:161], v[176:179], v[46:49]
	v_mfma_f32_16x16x32_bf16 v[38:41], v[150:153], v[184:187], v[38:41]
	v_mfma_f32_16x16x32_bf16 v[30:33], v[158:161], v[184:187], v[30:33]
	v_mfma_f32_16x16x32_bf16 v[22:25], v[150:153], v[210:213], v[22:25]
	v_mfma_f32_16x16x32_bf16 v[14:17], v[158:161], v[210:213], v[14:17]
	v_mfma_f32_16x16x32_bf16 v[6:9], v[150:153], v[218:221], v[6:9]
	v_mfma_f32_16x16x32_bf16 v[2:5], v[158:161], v[218:221], v[2:5]
	s_setprio 0
	s_barrier
	s_add_u32 s38, s38, 0x100
	s_addc_u32 s39, s39, 0
	s_add_u32 s15, s15, 0x100
	s_addc_u32 s21, s21, 0
	s_cmp_ge_u32 s37, s27
	s_mov_b32 s33, s37
	s_cbranch_scc0 .LBB0_977
	s_and_b64 vcc, exec, s[10:11]
	s_cbranch_vccz .LBB0_980
	s_barrier

.LBB0_1079:
	s_ashr_i32 s43, s42, 31
	s_lshl_b64 s[40:41], s[42:43], 20
	s_add_u32 s50, s19, s40
	s_addc_u32 s51, s28, s41
	s_and_b64 s[40:41], s[8:9], exec
	s_cselect_b32 s11, s51, s57
	s_cselect_b32 s33, s50, s56
	s_ashr_i32 s39, s38, 31
	s_lshl_b64 s[40:41], s[38:39], 20
	s_add_u32 s52, s29, s40
	s_addc_u32 s53, s34, s41
	s_and_b64 s[40:41], s[8:9], exec
	s_cselect_b32 s39, s53, s61
	s_cselect_b32 s40, s52, s60
	s_add_u32 s41, s60, 0x100
	v_mov_b32_e32 v2, 0
	s_addc_u32 s43, s61, 0
	s_mov_b32 s44, -2
	v_mov_b32_e32 v3, v2
	v_mov_b32_e32 v4, v2
	v_mov_b32_e32 v5, v2
	v_mov_b32_e32 v74, v2
	v_mov_b32_e32 v75, v2
	v_mov_b32_e32 v76, v2
	v_mov_b32_e32 v77, v2
	v_mov_b32_e32 v6, v2
	v_mov_b32_e32 v7, v2
	v_mov_b32_e32 v8, v2
	v_mov_b32_e32 v9, v2
	v_mov_b32_e32 v78, v2
	v_mov_b32_e32 v79, v2
	v_mov_b32_e32 v80, v2
	v_mov_b32_e32 v81, v2
	v_mov_b32_e32 v18, v2
	v_mov_b32_e32 v19, v2
	v_mov_b32_e32 v20, v2
	v_mov_b32_e32 v21, v2
	v_mov_b32_e32 v90, v2
	v_mov_b32_e32 v91, v2
	v_mov_b32_e32 v92, v2
	v_mov_b32_e32 v93, v2
	v_mov_b32_e32 v26, v2
	v_mov_b32_e32 v27, v2
	v_mov_b32_e32 v28, v2
	v_mov_b32_e32 v29, v2
	v_mov_b32_e32 v98, v2
	v_mov_b32_e32 v99, v2
	v_mov_b32_e32 v100, v2
	v_mov_b32_e32 v101, v2
	v_mov_b32_e32 v10, v2
	v_mov_b32_e32 v11, v2
	v_mov_b32_e32 v12, v2
	v_mov_b32_e32 v13, v2
	v_mov_b32_e32 v82, v2
	v_mov_b32_e32 v83, v2
	v_mov_b32_e32 v84, v2
	v_mov_b32_e32 v85, v2
	v_mov_b32_e32 v14, v2
	v_mov_b32_e32 v15, v2
	v_mov_b32_e32 v16, v2
	v_mov_b32_e32 v17, v2
	v_mov_b32_e32 v86, v2
	v_mov_b32_e32 v87, v2
	v_mov_b32_e32 v88, v2
	v_mov_b32_e32 v89, v2
	v_mov_b32_e32 v22, v2
	v_mov_b32_e32 v23, v2
	v_mov_b32_e32 v24, v2
	v_mov_b32_e32 v25, v2
	v_mov_b32_e32 v94, v2
	v_mov_b32_e32 v95, v2
	v_mov_b32_e32 v96, v2
	v_mov_b32_e32 v97, v2
	v_mov_b32_e32 v30, v2
	v_mov_b32_e32 v31, v2
	v_mov_b32_e32 v32, v2
	v_mov_b32_e32 v33, v2
	v_mov_b32_e32 v102, v2
	v_mov_b32_e32 v103, v2
	v_mov_b32_e32 v104, v2
	v_mov_b32_e32 v105, v2
	v_mov_b32_e32 v34, v2
	v_mov_b32_e32 v35, v2
	v_mov_b32_e32 v36, v2
	v_mov_b32_e32 v37, v2
	v_mov_b32_e32 v114, v2
	v_mov_b32_e32 v115, v2
	v_mov_b32_e32 v116, v2
	v_mov_b32_e32 v117, v2
	v_mov_b32_e32 v42, v2
	v_mov_b32_e32 v43, v2
	v_mov_b32_e32 v44, v2
	v_mov_b32_e32 v45, v2
	v_mov_b32_e32 v122, v2
	v_mov_b32_e32 v123, v2
	v_mov_b32_e32 v124, v2
	v_mov_b32_e32 v125, v2
	v_mov_b32_e32 v50, v2
	v_mov_b32_e32 v51, v2
	v_mov_b32_e32 v52, v2
	v_mov_b32_e32 v53, v2
	v_mov_b32_e32 v130, v2
	v_mov_b32_e32 v131, v2
	v_mov_b32_e32 v132, v2
	v_mov_b32_e32 v133, v2
	v_mov_b32_e32 v58, v2
	v_mov_b32_e32 v59, v2
	v_mov_b32_e32 v60, v2
	v_mov_b32_e32 v61, v2
	v_mov_b32_e32 v142, v2
	v_mov_b32_e32 v143, v2
	v_mov_b32_e32 v144, v2
	v_mov_b32_e32 v145, v2
	v_mov_b32_e32 v38, v2
	v_mov_b32_e32 v39, v2
	v_mov_b32_e32 v40, v2
	v_mov_b32_e32 v41, v2
	v_mov_b32_e32 v118, v2
	v_mov_b32_e32 v119, v2
	v_mov_b32_e32 v120, v2
	v_mov_b32_e32 v121, v2
	v_mov_b32_e32 v46, v2
	v_mov_b32_e32 v47, v2
	v_mov_b32_e32 v48, v2
	v_mov_b32_e32 v49, v2
	v_mov_b32_e32 v126, v2
	v_mov_b32_e32 v127, v2
	v_mov_b32_e32 v128, v2
	v_mov_b32_e32 v129, v2
	v_mov_b32_e32 v54, v2
	v_mov_b32_e32 v55, v2
	v_mov_b32_e32 v56, v2
	v_mov_b32_e32 v57, v2
	v_mov_b32_e32 v134, v2
	v_mov_b32_e32 v135, v2
	v_mov_b32_e32 v136, v2
	v_mov_b32_e32 v137, v2
	v_mov_b32_e32 v70, v2
	v_mov_b32_e32 v71, v2
	v_mov_b32_e32 v72, v2
	v_mov_b32_e32 v73, v2
	v_mov_b32_e32 v146, v2
	v_mov_b32_e32 v147, v2
	v_mov_b32_e32 v148, v2
	v_mov_b32_e32 v149, v2
	v_add_u32_e32 v253, 0x10000, v223
.LBB0_1080:
	s_add_u32 s60, s56, 0x100
	s_addc_u32 s61, s57, 0
	s_add_i32 s45, 0, 0x10000
	s_cmp_eq_u32 s44, 28
	s_cselect_b32 s65, s11, s61
	s_cselect_b32 s64, s33, s60
	s_cselect_b32 s63, s39, s43
	s_cselect_b32 s62, s40, s41
	s_add_i32 s55, 0, 0x14000
	ds_read_b128 v[62:65], v253
	ds_read_b128 v[66:69], v253 offset:1024
	ds_read_b128 v[106:109], v253 offset:2048
	ds_read_b128 v[110:113], v253 offset:3072
	ds_read_b128 v[138:141], v253 offset:16384
	ds_read_b128 v[150:153], v253 offset:17408
	ds_read_b128 v[154:157], v253 offset:18432
	ds_read_b128 v[158:161], v253 offset:19456
	s_add_i32 m0, s46, 0xc000
	ds_read_b128 v[162:165], v227
	ds_read_b128 v[166:169], v227 offset:1024
	ds_read_b128 v[170:173], v227 offset:2048
	ds_read_b128 v[174:177], v227 offset:3072
	ds_read_b128 v[178:181], v227 offset:4096
	ds_read_b128 v[182:185], v227 offset:5120
	ds_read_b128 v[186:189], v227 offset:6144
	ds_read_b128 v[190:193], v227 offset:7168
	global_load_lds_dwordx4 v210, s[56:57]
	s_add_i32 m0, s46, 0xe000
	s_nop 0
	global_load_lds_dwordx4 v212, s[56:57]
	s_waitcnt vmcnt(8)
	s_waitcnt lgkmcnt(0)
	s_barrier
	s_setprio 1
	s_waitcnt lgkmcnt(0)
	v_mfma_f32_16x16x32_bf16 v[146:149], v[62:65], v[162:165], v[146:149]
	v_mfma_f32_16x16x32_bf16 v[70:73], v[106:109], v[162:165], v[70:73]
	v_mfma_f32_16x16x32_bf16 v[134:137], v[62:65], v[170:173], v[134:137]
	v_mfma_f32_16x16x32_bf16 v[54:57], v[106:109], v[170:173], v[54:57]
	v_mfma_f32_16x16x32_bf16 v[126:129], v[62:65], v[178:181], v[126:129]
	v_mfma_f32_16x16x32_bf16 v[46:49], v[106:109], v[178:181], v[46:49]
	v_mfma_f32_16x16x32_bf16 v[118:121], v[62:65], v[186:189], v[118:121]
	v_mfma_f32_16x16x32_bf16 v[38:41], v[106:109], v[186:189], v[38:41]
	v_mfma_f32_16x16x32_bf16 v[146:149], v[66:69], v[166:169], v[146:149]
	v_mfma_f32_16x16x32_bf16 v[70:73], v[110:113], v[166:169], v[70:73]
	v_mfma_f32_16x16x32_bf16 v[134:137], v[66:69], v[174:177], v[134:137]
	v_mfma_f32_16x16x32_bf16 v[54:57], v[110:113], v[174:177], v[54:57]
	v_mfma_f32_16x16x32_bf16 v[126:129], v[66:69], v[182:185], v[126:129]
	v_mfma_f32_16x16x32_bf16 v[46:49], v[110:113], v[182:185], v[46:49]
	v_mfma_f32_16x16x32_bf16 v[118:121], v[66:69], v[190:193], v[118:121]
	v_mfma_f32_16x16x32_bf16 v[38:41], v[110:113], v[190:193], v[38:41]
	s_setprio 0
	s_setprio 1
	v_mfma_f32_16x16x32_bf16 v[142:145], v[138:141], v[162:165], v[142:145]
	v_mfma_f32_16x16x32_bf16 v[58:61], v[154:157], v[162:165], v[58:61]
	v_mfma_f32_16x16x32_bf16 v[130:133], v[138:141], v[170:173], v[130:133]
	v_mfma_f32_16x16x32_bf16 v[50:53], v[154:157], v[170:173], v[50:53]
	v_mfma_f32_16x16x32_bf16 v[122:125], v[138:141], v[178:181], v[122:125]
	v_mfma_f32_16x16x32_bf16 v[42:45], v[154:157], v[178:181], v[42:45]
	v_mfma_f32_16x16x32_bf16 v[114:117], v[138:141], v[186:189], v[114:117]
	v_mfma_f32_16x16x32_bf16 v[34:37], v[154:157], v[186:189], v[34:37]
	v_mfma_f32_16x16x32_bf16 v[142:145], v[150:153], v[166:169], v[142:145]
	v_mfma_f32_16x16x32_bf16 v[58:61], v[158:161], v[166:169], v[58:61]
	v_mfma_f32_16x16x32_bf16 v[130:133], v[150:153], v[174:177], v[130:133]
	v_mfma_f32_16x16x32_bf16 v[50:53], v[158:161], v[174:177], v[50:53]
	v_mfma_f32_16x16x32_bf16 v[122:125], v[150:153], v[182:185], v[122:125]
	v_mfma_f32_16x16x32_bf16 v[42:45], v[158:161], v[182:185], v[42:45]
	v_mfma_f32_16x16x32_bf16 v[114:117], v[150:153], v[190:193], v[114:117]
	v_mfma_f32_16x16x32_bf16 v[34:37], v[158:161], v[190:193], v[34:37]
	s_setprio 0
	s_barrier
	s_add_i32 s45, s45, s35
	s_mov_b32 m0, s45
	ds_read_b128 v[162:165], v227 offset:16384
	ds_read_b128 v[166:169], v227 offset:17408
	ds_read_b128 v[170:173], v227 offset:18432
	ds_read_b128 v[174:177], v227 offset:19456
	ds_read_b128 v[178:181], v227 offset:20480
	ds_read_b128 v[182:185], v227 offset:21504
	ds_read_b128 v[186:189], v227 offset:22528
	ds_read_b128 v[190:193], v227 offset:23552
	global_load_lds_dwordx4 v0, s[62:63]
	s_add_i32 m0, s45, 0x2000
	s_add_u32 s56, s62, 0x80000
	s_addc_u32 s57, s63, 0
	s_add_i32 s45, s55, s35
	global_load_lds_dwordx4 v208, s[62:63]
	s_mov_b32 m0, s45
	s_nop 0
	global_load_lds_dwordx4 v0, s[56:57]
	s_add_i32 m0, s45, 0x2000
	s_nop 0
	global_load_lds_dwordx4 v208, s[56:57]
	s_mov_b32 m0, s46
	s_nop 0
	global_load_lds_dwordx4 v204, s[64:65]
	s_mov_b32 m0, s66
	s_nop 0
	global_load_lds_dwordx4 v206, s[64:65]
	s_waitcnt vmcnt(8)
	s_waitcnt lgkmcnt(0)
	s_barrier
	s_setprio 1
	s_waitcnt lgkmcnt(0)
	v_mfma_f32_16x16x32_bf16 v[102:105], v[62:65], v[162:165], v[102:105]
	v_mfma_f32_16x16x32_bf16 v[30:33], v[106:109], v[162:165], v[30:33]
	v_mfma_f32_16x16x32_bf16 v[94:97], v[62:65], v[170:173], v[94:97]
	v_mfma_f32_16x16x32_bf16 v[22:25], v[106:109], v[170:173], v[22:25]
	v_mfma_f32_16x16x32_bf16 v[86:89], v[62:65], v[178:181], v[86:89]
	v_mfma_f32_16x16x32_bf16 v[14:17], v[106:109], v[178:181], v[14:17]
	v_mfma_f32_16x16x32_bf16 v[10:13], v[106:109], v[186:189], v[10:13]
	v_mfma_f32_16x16x32_bf16 v[102:105], v[66:69], v[166:169], v[102:105]
	v_mfma_f32_16x16x32_bf16 v[30:33], v[110:113], v[166:169], v[30:33]
	v_mfma_f32_16x16x32_bf16 v[94:97], v[66:69], v[174:177], v[94:97]
	v_mfma_f32_16x16x32_bf16 v[22:25], v[110:113], v[174:177], v[22:25]
	v_mfma_f32_16x16x32_bf16 v[86:89], v[66:69], v[182:185], v[86:89]
	v_mfma_f32_16x16x32_bf16 v[14:17], v[110:113], v[182:185], v[14:17]
	v_mfma_f32_16x16x32_bf16 v[62:65], v[62:65], v[186:189], v[82:85]
	v_mfma_f32_16x16x32_bf16 v[10:13], v[110:113], v[190:193], v[10:13]
	v_mfma_f32_16x16x32_bf16 v[62:65], v[66:69], v[190:193], v[62:65]
	s_setprio 0
	s_setprio 1
	v_mfma_f32_16x16x32_bf16 v[26:29], v[154:157], v[162:165], v[26:29]
	v_mfma_f32_16x16x32_bf16 v[82:85], v[138:141], v[170:173], v[90:93]
	v_mfma_f32_16x16x32_bf16 v[18:21], v[154:157], v[170:173], v[18:21]
	v_mfma_f32_16x16x32_bf16 v[78:81], v[138:141], v[178:181], v[78:81]
	v_mfma_f32_16x16x32_bf16 v[6:9], v[154:157], v[178:181], v[6:9]
	v_mfma_f32_16x16x32_bf16 v[74:77], v[138:141], v[186:189], v[74:77]
	v_mfma_f32_16x16x32_bf16 v[2:5], v[154:157], v[186:189], v[2:5]
	v_mfma_f32_16x16x32_bf16 v[66:69], v[138:141], v[162:165], v[98:101]
	v_mfma_f32_16x16x32_bf16 v[26:29], v[158:161], v[166:169], v[26:29]
	v_mfma_f32_16x16x32_bf16 v[90:93], v[150:153], v[174:177], v[82:85]
	v_mfma_f32_16x16x32_bf16 v[18:21], v[158:161], v[174:177], v[18:21]
	v_mfma_f32_16x16x32_bf16 v[78:81], v[150:153], v[182:185], v[78:81]
	v_mfma_f32_16x16x32_bf16 v[6:9], v[158:161], v[182:185], v[6:9]
	v_mfma_f32_16x16x32_bf16 v[74:77], v[150:153], v[190:193], v[74:77]
	v_mfma_f32_16x16x32_bf16 v[2:5], v[158:161], v[190:193], v[2:5]
	v_mfma_f32_16x16x32_bf16 v[66:69], v[150:153], v[166:169], v[66:69]
	s_setprio 0
	s_barrier
	s_add_i32 s45, 0, 0x18000
	s_add_i32 s55, 0, 0x1c000
	ds_read_b128 v[82:85], v253 offset:32768
	ds_read_b128 v[98:101], v253 offset:33792
	ds_read_b128 v[106:109], v253 offset:34816
	ds_read_b128 v[110:113], v253 offset:35840
	ds_read_b128 v[138:141], v253 offset:49152
	ds_read_b128 v[150:153], v253 offset:50176
	ds_read_b128 v[154:157], v253 offset:51200
	ds_read_b128 v[158:161], v253 offset:52224
	s_add_u32 s56, s64, 0x4000
	s_addc_u32 s57, s65, 0
	s_mov_b32 m0, s67
	ds_read_b128 v[162:165], v227 offset:32768
	ds_read_b128 v[166:169], v227 offset:33792
	ds_read_b128 v[170:173], v227 offset:34816
	ds_read_b128 v[174:177], v227 offset:35840
	ds_read_b128 v[178:181], v227 offset:36864
	ds_read_b128 v[182:185], v227 offset:37888
	ds_read_b128 v[186:189], v227 offset:38912
	ds_read_b128 v[190:193], v227 offset:39936
	global_load_lds_dwordx4 v204, s[56:57]
	s_mov_b32 m0, s68
	s_nop 0
	global_load_lds_dwordx4 v206, s[56:57]
	s_waitcnt vmcnt(8)
	s_waitcnt lgkmcnt(0)
	s_barrier
	s_setprio 1
	s_waitcnt lgkmcnt(0)
	v_mfma_f32_16x16x32_bf16 v[146:149], v[82:85], v[162:165], v[146:149]
	v_mfma_f32_16x16x32_bf16 v[70:73], v[106:109], v[162:165], v[70:73]
	v_mfma_f32_16x16x32_bf16 v[134:137], v[82:85], v[170:173], v[134:137]
	v_mfma_f32_16x16x32_bf16 v[54:57], v[106:109], v[170:173], v[54:57]
	v_mfma_f32_16x16x32_bf16 v[126:129], v[82:85], v[178:181], v[126:129]
	v_mfma_f32_16x16x32_bf16 v[46:49], v[106:109], v[178:181], v[46:49]
	v_mfma_f32_16x16x32_bf16 v[118:121], v[82:85], v[186:189], v[118:121]
	v_mfma_f32_16x16x32_bf16 v[38:41], v[106:109], v[186:189], v[38:41]
	v_mfma_f32_16x16x32_bf16 v[146:149], v[98:101], v[166:169], v[146:149]
	v_mfma_f32_16x16x32_bf16 v[70:73], v[110:113], v[166:169], v[70:73]
	v_mfma_f32_16x16x32_bf16 v[134:137], v[98:101], v[174:177], v[134:137]
	v_mfma_f32_16x16x32_bf16 v[54:57], v[110:113], v[174:177], v[54:57]
	v_mfma_f32_16x16x32_bf16 v[126:129], v[98:101], v[182:185], v[126:129]
	v_mfma_f32_16x16x32_bf16 v[46:49], v[110:113], v[182:185], v[46:49]
	v_mfma_f32_16x16x32_bf16 v[118:121], v[98:101], v[190:193], v[118:121]
	v_mfma_f32_16x16x32_bf16 v[38:41], v[110:113], v[190:193], v[38:41]
	s_setprio 0
	s_setprio 1
	v_mfma_f32_16x16x32_bf16 v[142:145], v[138:141], v[162:165], v[142:145]
	v_mfma_f32_16x16x32_bf16 v[58:61], v[154:157], v[162:165], v[58:61]
	v_mfma_f32_16x16x32_bf16 v[130:133], v[138:141], v[170:173], v[130:133]
	v_mfma_f32_16x16x32_bf16 v[50:53], v[154:157], v[170:173], v[50:53]
	v_mfma_f32_16x16x32_bf16 v[122:125], v[138:141], v[178:181], v[122:125]
	v_mfma_f32_16x16x32_bf16 v[42:45], v[154:157], v[178:181], v[42:45]
	v_mfma_f32_16x16x32_bf16 v[114:117], v[138:141], v[186:189], v[114:117]
	v_mfma_f32_16x16x32_bf16 v[34:37], v[154:157], v[186:189], v[34:37]
	v_mfma_f32_16x16x32_bf16 v[142:145], v[150:153], v[166:169], v[142:145]
	v_mfma_f32_16x16x32_bf16 v[58:61], v[158:161], v[166:169], v[58:61]
	v_mfma_f32_16x16x32_bf16 v[130:133], v[150:153], v[174:177], v[130:133]
	v_mfma_f32_16x16x32_bf16 v[50:53], v[158:161], v[174:177], v[50:53]
	v_mfma_f32_16x16x32_bf16 v[122:125], v[150:153], v[182:185], v[122:125]
	v_mfma_f32_16x16x32_bf16 v[42:45], v[158:161], v[182:185], v[42:45]
	v_mfma_f32_16x16x32_bf16 v[114:117], v[150:153], v[190:193], v[114:117]
	v_mfma_f32_16x16x32_bf16 v[34:37], v[158:161], v[190:193], v[34:37]
	s_setprio 0
	s_barrier
	s_add_u32 s100, s56, 0xffffc080
	s_addc_u32 s101, s57, -1
	s_add_u32 s98, s62, 0x80
	s_addc_u32 s99, s63, 0
	s_add_i32 s45, s45, s35
	s_mov_b32 m0, s45
	ds_read_b128 v[162:165], v227 offset:49152
	ds_read_b128 v[166:169], v227 offset:50176
	ds_read_b128 v[170:173], v227 offset:51200
	ds_read_b128 v[174:177], v227 offset:52224
	ds_read_b128 v[178:181], v227 offset:53248
	ds_read_b128 v[182:185], v227 offset:54272
	ds_read_b128 v[186:189], v227 offset:55296
	ds_read_b128 v[190:193], v227 offset:56320
	global_load_lds_dwordx4 v0, s[98:99]
	s_add_i32 m0, s45, 0x2000
	s_add_u32 s56, s62, 0x80080
	s_addc_u32 s57, s63, 0
	s_add_i32 s45, s55, s35
	global_load_lds_dwordx4 v208, s[98:99]
	s_mov_b32 m0, s45
	s_nop 0
	global_load_lds_dwordx4 v0, s[56:57]
	s_add_i32 m0, s45, 0x2000
	s_nop 0
	global_load_lds_dwordx4 v208, s[56:57]
	s_mov_b32 m0, s71
	s_nop 0
	global_load_lds_dwordx4 v204, s[100:101]
	s_mov_b32 m0, s74
	s_nop 0
	global_load_lds_dwordx4 v206, s[100:101]
	s_waitcnt vmcnt(8)
	s_waitcnt lgkmcnt(0)
	s_barrier
	s_setprio 1
	s_waitcnt lgkmcnt(0)
	v_mfma_f32_16x16x32_bf16 v[102:105], v[82:85], v[162:165], v[102:105]
	v_mfma_f32_16x16x32_bf16 v[30:33], v[106:109], v[162:165], v[30:33]
	v_mfma_f32_16x16x32_bf16 v[94:97], v[82:85], v[170:173], v[94:97]
	v_mfma_f32_16x16x32_bf16 v[22:25], v[106:109], v[170:173], v[22:25]
	v_mfma_f32_16x16x32_bf16 v[86:89], v[82:85], v[178:181], v[86:89]
	v_mfma_f32_16x16x32_bf16 v[14:17], v[106:109], v[178:181], v[14:17]
	v_mfma_f32_16x16x32_bf16 v[62:65], v[82:85], v[186:189], v[62:65]
	v_mfma_f32_16x16x32_bf16 v[10:13], v[106:109], v[186:189], v[10:13]
	v_mfma_f32_16x16x32_bf16 v[102:105], v[98:101], v[166:169], v[102:105]
	v_mfma_f32_16x16x32_bf16 v[30:33], v[110:113], v[166:169], v[30:33]
	v_mfma_f32_16x16x32_bf16 v[94:97], v[98:101], v[174:177], v[94:97]
	v_mfma_f32_16x16x32_bf16 v[22:25], v[110:113], v[174:177], v[22:25]
	v_mfma_f32_16x16x32_bf16 v[86:89], v[98:101], v[182:185], v[86:89]
	v_mfma_f32_16x16x32_bf16 v[14:17], v[110:113], v[182:185], v[14:17]
	v_mfma_f32_16x16x32_bf16 v[82:85], v[98:101], v[190:193], v[62:65]
	v_mfma_f32_16x16x32_bf16 v[10:13], v[110:113], v[190:193], v[10:13]
	s_setprio 0
	s_setprio 1
	v_mfma_f32_16x16x32_bf16 v[62:65], v[138:141], v[162:165], v[66:69]
	v_mfma_f32_16x16x32_bf16 v[98:101], v[150:153], v[166:169], v[62:65]
	v_mfma_f32_16x16x32_bf16 v[62:65], v[138:141], v[170:173], v[90:93]
	v_mfma_f32_16x16x32_bf16 v[90:93], v[150:153], v[174:177], v[62:65]
	v_mfma_f32_16x16x32_bf16 v[62:65], v[138:141], v[178:181], v[78:81]
	v_mfma_f32_16x16x32_bf16 v[26:29], v[154:157], v[162:165], v[26:29]
	v_mfma_f32_16x16x32_bf16 v[18:21], v[154:157], v[170:173], v[18:21]
	v_mfma_f32_16x16x32_bf16 v[78:81], v[150:153], v[182:185], v[62:65]
	v_mfma_f32_16x16x32_bf16 v[6:9], v[154:157], v[178:181], v[6:9]
	v_mfma_f32_16x16x32_bf16 v[62:65], v[138:141], v[186:189], v[74:77]
	v_mfma_f32_16x16x32_bf16 v[2:5], v[154:157], v[186:189], v[2:5]
	v_mfma_f32_16x16x32_bf16 v[26:29], v[158:161], v[166:169], v[26:29]
	v_mfma_f32_16x16x32_bf16 v[18:21], v[158:161], v[174:177], v[18:21]
	v_mfma_f32_16x16x32_bf16 v[6:9], v[158:161], v[182:185], v[6:9]
	v_mfma_f32_16x16x32_bf16 v[74:77], v[150:153], v[190:193], v[62:65]
	v_mfma_f32_16x16x32_bf16 v[2:5], v[158:161], v[190:193], v[2:5]
	s_setprio 0
	s_barrier
	s_add_i32 s44, s44, 2
	s_add_u32 s41, s41, 0x100
	s_addc_u32 s43, s43, 0
	s_cmp_gt_u32 s44, 29
	s_mov_b64 s[56:57], s[60:61]
	s_cbranch_scc0 .LBB0_1080
	s_and_b64 vcc, exec, s[24:25]
	s_cbranch_vccz .LBB0_1083
	s_barrier

.LBB0_1185:
	s_add_i32 s13, s55, -2
	s_add_u32 s33, s24, 0x100
	v_mov_b32_e32 v2, 0
	s_addc_u32 s40, s25, 0
	s_mov_b32 s26, 0
	v_mov_b32_e32 v3, v2
	v_mov_b32_e32 v4, v2
	v_mov_b32_e32 v5, v2
	v_mov_b32_e32 v6, v2
	v_mov_b32_e32 v7, v2
	v_mov_b32_e32 v8, v2
	v_mov_b32_e32 v9, v2
	v_mov_b32_e32 v14, v2
	v_mov_b32_e32 v15, v2
	v_mov_b32_e32 v16, v2
	v_mov_b32_e32 v17, v2
	v_mov_b32_e32 v22, v2
	v_mov_b32_e32 v23, v2
	v_mov_b32_e32 v24, v2
	v_mov_b32_e32 v25, v2
	v_mov_b32_e32 v30, v2
	v_mov_b32_e32 v31, v2
	v_mov_b32_e32 v32, v2
	v_mov_b32_e32 v33, v2
	v_mov_b32_e32 v38, v2
	v_mov_b32_e32 v39, v2
	v_mov_b32_e32 v40, v2
	v_mov_b32_e32 v41, v2
	v_mov_b32_e32 v46, v2
	v_mov_b32_e32 v47, v2
	v_mov_b32_e32 v48, v2
	v_mov_b32_e32 v49, v2
	v_mov_b32_e32 v54, v2
	v_mov_b32_e32 v55, v2
	v_mov_b32_e32 v56, v2
	v_mov_b32_e32 v57, v2
	v_mov_b32_e32 v10, v2
	v_mov_b32_e32 v11, v2
	v_mov_b32_e32 v12, v2
	v_mov_b32_e32 v13, v2
	v_mov_b32_e32 v18, v2
	v_mov_b32_e32 v19, v2
	v_mov_b32_e32 v20, v2
	v_mov_b32_e32 v21, v2
	v_mov_b32_e32 v26, v2
	v_mov_b32_e32 v27, v2
	v_mov_b32_e32 v28, v2
	v_mov_b32_e32 v29, v2
	v_mov_b32_e32 v34, v2
	v_mov_b32_e32 v35, v2
	v_mov_b32_e32 v36, v2
	v_mov_b32_e32 v37, v2
	v_mov_b32_e32 v42, v2
	v_mov_b32_e32 v43, v2
	v_mov_b32_e32 v44, v2
	v_mov_b32_e32 v45, v2
	v_mov_b32_e32 v50, v2
	v_mov_b32_e32 v51, v2
	v_mov_b32_e32 v52, v2
	v_mov_b32_e32 v53, v2
	v_mov_b32_e32 v58, v2
	v_mov_b32_e32 v59, v2
	v_mov_b32_e32 v60, v2
	v_mov_b32_e32 v61, v2
	v_mov_b32_e32 v62, v2
	v_mov_b32_e32 v63, v2
	v_mov_b32_e32 v64, v2
	v_mov_b32_e32 v65, v2
	v_mov_b32_e32 v66, v2
	v_mov_b32_e32 v67, v2
	v_mov_b32_e32 v68, v2
	v_mov_b32_e32 v69, v2
	v_mov_b32_e32 v70, v2
	v_mov_b32_e32 v71, v2
	v_mov_b32_e32 v72, v2
	v_mov_b32_e32 v73, v2
	v_mov_b32_e32 v74, v2
	v_mov_b32_e32 v75, v2
	v_mov_b32_e32 v76, v2
	v_mov_b32_e32 v77, v2
	v_mov_b32_e32 v82, v2
	v_mov_b32_e32 v83, v2
	v_mov_b32_e32 v84, v2
	v_mov_b32_e32 v85, v2
	v_mov_b32_e32 v94, v2
	v_mov_b32_e32 v95, v2
	v_mov_b32_e32 v96, v2
	v_mov_b32_e32 v97, v2
	v_mov_b32_e32 v114, v2
	v_mov_b32_e32 v115, v2
	v_mov_b32_e32 v116, v2
	v_mov_b32_e32 v117, v2
	v_mov_b32_e32 v122, v2
	v_mov_b32_e32 v123, v2
	v_mov_b32_e32 v124, v2
	v_mov_b32_e32 v125, v2
	v_mov_b32_e32 v130, v2
	v_mov_b32_e32 v131, v2
	v_mov_b32_e32 v132, v2
	v_mov_b32_e32 v133, v2
	v_mov_b32_e32 v78, v2
	v_mov_b32_e32 v79, v2
	v_mov_b32_e32 v80, v2
	v_mov_b32_e32 v81, v2
	v_mov_b32_e32 v86, v2
	v_mov_b32_e32 v87, v2
	v_mov_b32_e32 v88, v2
	v_mov_b32_e32 v89, v2
	v_mov_b32_e32 v90, v2
	v_mov_b32_e32 v91, v2
	v_mov_b32_e32 v92, v2
	v_mov_b32_e32 v93, v2
	v_mov_b32_e32 v98, v2
	v_mov_b32_e32 v99, v2
	v_mov_b32_e32 v100, v2
	v_mov_b32_e32 v101, v2
	v_mov_b32_e32 v126, v2
	v_mov_b32_e32 v127, v2
	v_mov_b32_e32 v128, v2
	v_mov_b32_e32 v129, v2
	v_mov_b32_e32 v134, v2
	v_mov_b32_e32 v135, v2
	v_mov_b32_e32 v136, v2
	v_mov_b32_e32 v137, v2
	v_mov_b32_e32 v138, v2
	v_mov_b32_e32 v139, v2
	v_mov_b32_e32 v140, v2
	v_mov_b32_e32 v141, v2
	v_mov_b32_e32 v142, v2
	v_mov_b32_e32 v143, v2
	v_mov_b32_e32 v144, v2
	v_mov_b32_e32 v145, v2
	v_add_u32_e32 v253, 0x10000, v190
.LBB0_1186:
	s_add_i32 s41, s26, 2
	s_add_u32 s24, s22, 0x100
	s_addc_u32 s25, s23, 0
	s_add_i32 s44, 0, 0x10000
	s_cmp_eq_u32 s13, s26
	s_cselect_b32 s31, s15, s25
	s_cselect_b32 s30, s14, s24
	s_cselect_b32 s27, s17, s40
	s_cselect_b32 s26, s16, s33
	s_add_i32 s45, 0, 0x14000
	ds_read_b128 v[102:105], v253
	ds_read_b128 v[106:109], v253 offset:1024
	ds_read_b128 v[110:113], v253 offset:2048
	ds_read_b128 v[118:121], v253 offset:3072
	ds_read_b128 v[146:149], v253 offset:16384
	ds_read_b128 v[150:153], v253 offset:17408
	ds_read_b128 v[154:157], v253 offset:18432
	ds_read_b128 v[158:161], v253 offset:19456
	s_add_i32 m0, s34, 0xc000
	ds_read_b128 v[162:165], v192
	ds_read_b128 v[176:179], v192 offset:1024
	ds_read_b128 v[180:183], v192 offset:2048
	ds_read_b128 v[184:187], v192 offset:3072
	ds_read_b128 v[204:207], v192 offset:4096
	ds_read_b128 v[208:211], v192 offset:5120
	ds_read_b128 v[212:215], v192 offset:6144
	ds_read_b128 v[216:219], v192 offset:7168
	global_load_lds_dwordx4 v172, s[22:23]
	s_add_i32 m0, s34, 0xe000
	s_nop 0
	global_load_lds_dwordx4 v174, s[22:23]
	s_waitcnt vmcnt(8)
	s_waitcnt lgkmcnt(0)
	s_barrier
	s_setprio 1
	s_waitcnt lgkmcnt(0)
	v_mfma_f32_16x16x32_bf16 v[142:145], v[102:105], v[162:165], v[142:145]
	v_mfma_f32_16x16x32_bf16 v[138:141], v[110:113], v[162:165], v[138:141]
	v_mfma_f32_16x16x32_bf16 v[134:137], v[102:105], v[180:183], v[134:137]
	v_mfma_f32_16x16x32_bf16 v[126:129], v[110:113], v[180:183], v[126:129]
	v_mfma_f32_16x16x32_bf16 v[98:101], v[102:105], v[204:207], v[98:101]
	v_mfma_f32_16x16x32_bf16 v[90:93], v[110:113], v[204:207], v[90:93]
	v_mfma_f32_16x16x32_bf16 v[86:89], v[102:105], v[212:215], v[86:89]
	v_mfma_f32_16x16x32_bf16 v[78:81], v[110:113], v[212:215], v[78:81]
	v_mfma_f32_16x16x32_bf16 v[142:145], v[106:109], v[176:179], v[142:145]
	v_mfma_f32_16x16x32_bf16 v[138:141], v[118:121], v[176:179], v[138:141]
	v_mfma_f32_16x16x32_bf16 v[134:137], v[106:109], v[184:187], v[134:137]
	v_mfma_f32_16x16x32_bf16 v[126:129], v[118:121], v[184:187], v[126:129]
	v_mfma_f32_16x16x32_bf16 v[98:101], v[106:109], v[208:211], v[98:101]
	v_mfma_f32_16x16x32_bf16 v[90:93], v[118:121], v[208:211], v[90:93]
	v_mfma_f32_16x16x32_bf16 v[86:89], v[106:109], v[216:219], v[86:89]
	v_mfma_f32_16x16x32_bf16 v[78:81], v[118:121], v[216:219], v[78:81]
	s_setprio 0
	s_setprio 1
	v_mfma_f32_16x16x32_bf16 v[130:133], v[146:149], v[162:165], v[130:133]
	v_mfma_f32_16x16x32_bf16 v[122:125], v[154:157], v[162:165], v[122:125]
	v_mfma_f32_16x16x32_bf16 v[114:117], v[146:149], v[180:183], v[114:117]
	v_mfma_f32_16x16x32_bf16 v[94:97], v[154:157], v[180:183], v[94:97]
	v_mfma_f32_16x16x32_bf16 v[82:85], v[146:149], v[204:207], v[82:85]
	v_mfma_f32_16x16x32_bf16 v[74:77], v[154:157], v[204:207], v[74:77]
	v_mfma_f32_16x16x32_bf16 v[70:73], v[146:149], v[212:215], v[70:73]
	v_mfma_f32_16x16x32_bf16 v[66:69], v[154:157], v[212:215], v[66:69]
	v_mfma_f32_16x16x32_bf16 v[130:133], v[150:153], v[176:179], v[130:133]
	v_mfma_f32_16x16x32_bf16 v[122:125], v[158:161], v[176:179], v[122:125]
	v_mfma_f32_16x16x32_bf16 v[114:117], v[150:153], v[184:187], v[114:117]
	v_mfma_f32_16x16x32_bf16 v[94:97], v[158:161], v[184:187], v[94:97]
	v_mfma_f32_16x16x32_bf16 v[82:85], v[150:153], v[208:211], v[82:85]
	v_mfma_f32_16x16x32_bf16 v[74:77], v[158:161], v[208:211], v[74:77]
	v_mfma_f32_16x16x32_bf16 v[70:73], v[150:153], v[216:219], v[70:73]
	v_mfma_f32_16x16x32_bf16 v[66:69], v[158:161], v[216:219], v[66:69]
	s_setprio 0
	s_barrier
	s_add_i32 s22, s44, s29
	s_mov_b32 m0, s22
	ds_read_b128 v[162:165], v192 offset:16384
	ds_read_b128 v[176:179], v192 offset:17408
	ds_read_b128 v[180:183], v192 offset:18432
	ds_read_b128 v[184:187], v192 offset:19456
	ds_read_b128 v[204:207], v192 offset:20480
	ds_read_b128 v[208:211], v192 offset:21504
	ds_read_b128 v[212:215], v192 offset:22528
	ds_read_b128 v[216:219], v192 offset:23552
	global_load_lds_dwordx4 v0, s[26:27]
	s_add_i32 m0, s22, 0x2000
	s_add_u32 s22, s26, 0x160000
	s_addc_u32 s23, s27, 0
	s_add_i32 s44, s45, s29
	global_load_lds_dwordx4 v170, s[26:27]
	s_mov_b32 m0, s44
	s_nop 0
	global_load_lds_dwordx4 v0, s[22:23]
	s_add_i32 m0, s44, 0x2000
	s_nop 0
	global_load_lds_dwordx4 v170, s[22:23]
	s_mov_b32 m0, s34
	s_nop 0
	global_load_lds_dwordx4 v166, s[30:31]
	s_mov_b32 m0, s35
	s_nop 0
	global_load_lds_dwordx4 v168, s[30:31]
	s_waitcnt vmcnt(8)
	s_waitcnt lgkmcnt(0)
	s_barrier
	s_setprio 1
	s_waitcnt lgkmcnt(0)
	v_mfma_f32_16x16x32_bf16 v[62:65], v[102:105], v[162:165], v[62:65]
	v_mfma_f32_16x16x32_bf16 v[58:61], v[110:113], v[162:165], v[58:61]
	v_mfma_f32_16x16x32_bf16 v[50:53], v[102:105], v[180:183], v[50:53]
	v_mfma_f32_16x16x32_bf16 v[42:45], v[110:113], v[180:183], v[42:45]
	v_mfma_f32_16x16x32_bf16 v[34:37], v[102:105], v[204:207], v[34:37]
	v_mfma_f32_16x16x32_bf16 v[26:29], v[110:113], v[204:207], v[26:29]
	v_mfma_f32_16x16x32_bf16 v[18:21], v[102:105], v[212:215], v[18:21]
	v_mfma_f32_16x16x32_bf16 v[10:13], v[110:113], v[212:215], v[10:13]
	v_mfma_f32_16x16x32_bf16 v[62:65], v[106:109], v[176:179], v[62:65]
	v_mfma_f32_16x16x32_bf16 v[58:61], v[118:121], v[176:179], v[58:61]
	v_mfma_f32_16x16x32_bf16 v[50:53], v[106:109], v[184:187], v[50:53]
	v_mfma_f32_16x16x32_bf16 v[42:45], v[118:121], v[184:187], v[42:45]
	v_mfma_f32_16x16x32_bf16 v[34:37], v[106:109], v[208:211], v[34:37]
	v_mfma_f32_16x16x32_bf16 v[26:29], v[118:121], v[208:211], v[26:29]
	v_mfma_f32_16x16x32_bf16 v[18:21], v[106:109], v[216:219], v[18:21]
	v_mfma_f32_16x16x32_bf16 v[10:13], v[118:121], v[216:219], v[10:13]
	s_setprio 0
	s_setprio 1
	v_mfma_f32_16x16x32_bf16 v[54:57], v[146:149], v[162:165], v[54:57]
	v_mfma_f32_16x16x32_bf16 v[46:49], v[154:157], v[162:165], v[46:49]
	v_mfma_f32_16x16x32_bf16 v[38:41], v[146:149], v[180:183], v[38:41]
	v_mfma_f32_16x16x32_bf16 v[30:33], v[154:157], v[180:183], v[30:33]
	v_mfma_f32_16x16x32_bf16 v[22:25], v[146:149], v[204:207], v[22:25]
	v_mfma_f32_16x16x32_bf16 v[14:17], v[154:157], v[204:207], v[14:17]
	v_mfma_f32_16x16x32_bf16 v[6:9], v[146:149], v[212:215], v[6:9]
	v_mfma_f32_16x16x32_bf16 v[2:5], v[154:157], v[212:215], v[2:5]
	v_mfma_f32_16x16x32_bf16 v[54:57], v[150:153], v[176:179], v[54:57]
	v_mfma_f32_16x16x32_bf16 v[46:49], v[158:161], v[176:179], v[46:49]
	v_mfma_f32_16x16x32_bf16 v[38:41], v[150:153], v[184:187], v[38:41]
	v_mfma_f32_16x16x32_bf16 v[30:33], v[158:161], v[184:187], v[30:33]
	v_mfma_f32_16x16x32_bf16 v[22:25], v[150:153], v[208:211], v[22:25]
	v_mfma_f32_16x16x32_bf16 v[14:17], v[158:161], v[208:211], v[14:17]
	v_mfma_f32_16x16x32_bf16 v[6:9], v[150:153], v[216:219], v[6:9]
	v_mfma_f32_16x16x32_bf16 v[2:5], v[158:161], v[216:219], v[2:5]
	s_setprio 0
	s_barrier
	s_add_i32 s44, 0, 0x18000
	s_add_i32 s45, 0, 0x1c000
	ds_read_b128 v[102:105], v253 offset:32768
	ds_read_b128 v[106:109], v253 offset:33792
	ds_read_b128 v[110:113], v253 offset:34816
	ds_read_b128 v[118:121], v253 offset:35840
	ds_read_b128 v[146:149], v253 offset:49152
	ds_read_b128 v[150:153], v253 offset:50176
	ds_read_b128 v[154:157], v253 offset:51200
	ds_read_b128 v[158:161], v253 offset:52224
	s_add_u32 s22, s30, 0x160000
	s_addc_u32 s23, s31, 0
	s_mov_b32 m0, s36
	ds_read_b128 v[162:165], v192 offset:32768
	ds_read_b128 v[176:179], v192 offset:33792
	ds_read_b128 v[180:183], v192 offset:34816
	ds_read_b128 v[184:187], v192 offset:35840
	ds_read_b128 v[204:207], v192 offset:36864
	ds_read_b128 v[208:211], v192 offset:37888
	ds_read_b128 v[212:215], v192 offset:38912
	ds_read_b128 v[216:219], v192 offset:39936
	global_load_lds_dwordx4 v166, s[22:23]
	s_mov_b32 m0, s37
	s_nop 0
	global_load_lds_dwordx4 v168, s[22:23]
	s_waitcnt vmcnt(8)
	s_waitcnt lgkmcnt(0)
	s_barrier
	s_setprio 1
	s_waitcnt lgkmcnt(0)
	v_mfma_f32_16x16x32_bf16 v[142:145], v[102:105], v[162:165], v[142:145]
	v_mfma_f32_16x16x32_bf16 v[138:141], v[110:113], v[162:165], v[138:141]
	v_mfma_f32_16x16x32_bf16 v[134:137], v[102:105], v[180:183], v[134:137]
	v_mfma_f32_16x16x32_bf16 v[126:129], v[110:113], v[180:183], v[126:129]
	v_mfma_f32_16x16x32_bf16 v[98:101], v[102:105], v[204:207], v[98:101]
	v_mfma_f32_16x16x32_bf16 v[90:93], v[110:113], v[204:207], v[90:93]
	v_mfma_f32_16x16x32_bf16 v[86:89], v[102:105], v[212:215], v[86:89]
	v_mfma_f32_16x16x32_bf16 v[78:81], v[110:113], v[212:215], v[78:81]
	v_mfma_f32_16x16x32_bf16 v[142:145], v[106:109], v[176:179], v[142:145]
	v_mfma_f32_16x16x32_bf16 v[138:141], v[118:121], v[176:179], v[138:141]
	v_mfma_f32_16x16x32_bf16 v[134:137], v[106:109], v[184:187], v[134:137]
	v_mfma_f32_16x16x32_bf16 v[126:129], v[118:121], v[184:187], v[126:129]
	v_mfma_f32_16x16x32_bf16 v[98:101], v[106:109], v[208:211], v[98:101]
	v_mfma_f32_16x16x32_bf16 v[90:93], v[118:121], v[208:211], v[90:93]
	v_mfma_f32_16x16x32_bf16 v[86:89], v[106:109], v[216:219], v[86:89]
	v_mfma_f32_16x16x32_bf16 v[78:81], v[118:121], v[216:219], v[78:81]
	s_setprio 0
	s_setprio 1
	v_mfma_f32_16x16x32_bf16 v[130:133], v[146:149], v[162:165], v[130:133]
	v_mfma_f32_16x16x32_bf16 v[122:125], v[154:157], v[162:165], v[122:125]
	v_mfma_f32_16x16x32_bf16 v[114:117], v[146:149], v[180:183], v[114:117]
	v_mfma_f32_16x16x32_bf16 v[94:97], v[154:157], v[180:183], v[94:97]
	v_mfma_f32_16x16x32_bf16 v[82:85], v[146:149], v[204:207], v[82:85]
	v_mfma_f32_16x16x32_bf16 v[74:77], v[154:157], v[204:207], v[74:77]
	v_mfma_f32_16x16x32_bf16 v[70:73], v[146:149], v[212:215], v[70:73]
	v_mfma_f32_16x16x32_bf16 v[66:69], v[154:157], v[212:215], v[66:69]
	v_mfma_f32_16x16x32_bf16 v[130:133], v[150:153], v[176:179], v[130:133]
	v_mfma_f32_16x16x32_bf16 v[122:125], v[158:161], v[176:179], v[122:125]
	v_mfma_f32_16x16x32_bf16 v[114:117], v[150:153], v[184:187], v[114:117]
	v_mfma_f32_16x16x32_bf16 v[94:97], v[158:161], v[184:187], v[94:97]
	v_mfma_f32_16x16x32_bf16 v[82:85], v[150:153], v[208:211], v[82:85]
	v_mfma_f32_16x16x32_bf16 v[74:77], v[158:161], v[208:211], v[74:77]
	v_mfma_f32_16x16x32_bf16 v[70:73], v[150:153], v[216:219], v[70:73]
	v_mfma_f32_16x16x32_bf16 v[66:69], v[158:161], v[216:219], v[66:69]
	s_setprio 0
	s_barrier
	s_add_u32 s100, s22, 0xffea0080
	s_addc_u32 s101, s23, -1
	s_add_u32 s98, s26, 0x80
	s_addc_u32 s99, s27, 0
	s_add_i32 s22, s44, s29
	s_mov_b32 m0, s22
	ds_read_b128 v[162:165], v192 offset:49152
	ds_read_b128 v[176:179], v192 offset:50176
	ds_read_b128 v[180:183], v192 offset:51200
	ds_read_b128 v[184:187], v192 offset:52224
	ds_read_b128 v[204:207], v192 offset:53248
	ds_read_b128 v[208:211], v192 offset:54272
	ds_read_b128 v[212:215], v192 offset:55296
	ds_read_b128 v[216:219], v192 offset:56320
	global_load_lds_dwordx4 v0, s[98:99]
	s_add_i32 m0, s22, 0x2000
	s_add_u32 s22, s26, 0x160080
	s_addc_u32 s23, s27, 0
	s_add_i32 s26, s45, s29
	global_load_lds_dwordx4 v170, s[98:99]
	s_mov_b32 m0, s26
	s_nop 0
	global_load_lds_dwordx4 v0, s[22:23]
	s_add_i32 m0, s26, 0x2000
	s_nop 0
	global_load_lds_dwordx4 v170, s[22:23]
	s_mov_b32 m0, s42
	s_nop 0
	global_load_lds_dwordx4 v166, s[100:101]
	s_mov_b32 m0, s43
	s_nop 0
	global_load_lds_dwordx4 v168, s[100:101]
	s_waitcnt vmcnt(8)
	s_waitcnt lgkmcnt(0)
	s_barrier
	s_setprio 1
	s_waitcnt lgkmcnt(0)
	v_mfma_f32_16x16x32_bf16 v[62:65], v[102:105], v[162:165], v[62:65]
	v_mfma_f32_16x16x32_bf16 v[58:61], v[110:113], v[162:165], v[58:61]
	v_mfma_f32_16x16x32_bf16 v[50:53], v[102:105], v[180:183], v[50:53]
	v_mfma_f32_16x16x32_bf16 v[42:45], v[110:113], v[180:183], v[42:45]
	v_mfma_f32_16x16x32_bf16 v[34:37], v[102:105], v[204:207], v[34:37]
	v_mfma_f32_16x16x32_bf16 v[26:29], v[110:113], v[204:207], v[26:29]
	v_mfma_f32_16x16x32_bf16 v[18:21], v[102:105], v[212:215], v[18:21]
	v_mfma_f32_16x16x32_bf16 v[10:13], v[110:113], v[212:215], v[10:13]
	v_mfma_f32_16x16x32_bf16 v[62:65], v[106:109], v[176:179], v[62:65]
	v_mfma_f32_16x16x32_bf16 v[58:61], v[118:121], v[176:179], v[58:61]
	v_mfma_f32_16x16x32_bf16 v[50:53], v[106:109], v[184:187], v[50:53]
	v_mfma_f32_16x16x32_bf16 v[42:45], v[118:121], v[184:187], v[42:45]
	v_mfma_f32_16x16x32_bf16 v[34:37], v[106:109], v[208:211], v[34:37]
	v_mfma_f32_16x16x32_bf16 v[26:29], v[118:121], v[208:211], v[26:29]
	v_mfma_f32_16x16x32_bf16 v[18:21], v[106:109], v[216:219], v[18:21]
	v_mfma_f32_16x16x32_bf16 v[10:13], v[118:121], v[216:219], v[10:13]
	s_setprio 0
	s_setprio 1
	v_mfma_f32_16x16x32_bf16 v[54:57], v[146:149], v[162:165], v[54:57]
	v_mfma_f32_16x16x32_bf16 v[46:49], v[154:157], v[162:165], v[46:49]
	v_mfma_f32_16x16x32_bf16 v[38:41], v[146:149], v[180:183], v[38:41]
	v_mfma_f32_16x16x32_bf16 v[30:33], v[154:157], v[180:183], v[30:33]
	v_mfma_f32_16x16x32_bf16 v[22:25], v[146:149], v[204:207], v[22:25]
	v_mfma_f32_16x16x32_bf16 v[14:17], v[154:157], v[204:207], v[14:17]
	v_mfma_f32_16x16x32_bf16 v[6:9], v[146:149], v[212:215], v[6:9]
	v_mfma_f32_16x16x32_bf16 v[2:5], v[154:157], v[212:215], v[2:5]
	v_mfma_f32_16x16x32_bf16 v[54:57], v[150:153], v[176:179], v[54:57]
	v_mfma_f32_16x16x32_bf16 v[46:49], v[158:161], v[176:179], v[46:49]
	v_mfma_f32_16x16x32_bf16 v[38:41], v[150:153], v[184:187], v[38:41]
	v_mfma_f32_16x16x32_bf16 v[30:33], v[158:161], v[184:187], v[30:33]
	v_mfma_f32_16x16x32_bf16 v[22:25], v[150:153], v[208:211], v[22:25]
	v_mfma_f32_16x16x32_bf16 v[14:17], v[158:161], v[208:211], v[14:17]
	v_mfma_f32_16x16x32_bf16 v[6:9], v[150:153], v[216:219], v[6:9]
	v_mfma_f32_16x16x32_bf16 v[2:5], v[158:161], v[216:219], v[2:5]
	s_setprio 0
	s_barrier
	s_add_u32 s33, s33, 0x100
	s_addc_u32 s40, s40, 0
	s_cmp_ge_u32 s41, s55
	s_mov_b64 s[22:23], s[24:25]
	s_mov_b32 s26, s41
	s_cbranch_scc0 .LBB0_1186
	s_and_b64 vcc, exec, s[10:11]
	s_cbranch_vccz .LBB0_1189
	s_barrier

	.amdhsa_kernel _Z10fwd_kernel4Args
		.amdhsa_group_segment_fixed_size 0
		.amdhsa_private_segment_fixed_size 0
		.amdhsa_kernarg_size 584
		.amdhsa_user_sgpr_count 2
		.amdhsa_user_sgpr_dispatch_ptr 0
		.amdhsa_user_sgpr_queue_ptr 0
		.amdhsa_user_sgpr_kernarg_segment_ptr 1
		.amdhsa_user_sgpr_dispatch_id 0
		.amdhsa_user_sgpr_kernarg_preload_length 0
		.amdhsa_user_sgpr_kernarg_preload_offset 0
		.amdhsa_user_sgpr_private_segment_size 0
		.amdhsa_uses_dynamic_stack 0
		.amdhsa_enable_private_segment 0
		.amdhsa_system_sgpr_workgroup_id_x 1
		.amdhsa_system_sgpr_workgroup_id_y 0
		.amdhsa_system_sgpr_workgroup_id_z 0
		.amdhsa_system_sgpr_workgroup_info 0
		.amdhsa_system_vgpr_workitem_id 0
		.amdhsa_next_free_vgpr 256
		.amdhsa_next_free_sgpr 102
		.amdhsa_accum_offset 256
		.amdhsa_reserve_vcc 1
		.amdhsa_float_round_mode_32 0
		.amdhsa_float_round_mode_16_64 0
		.amdhsa_float_denorm_mode_32 3
		.amdhsa_float_denorm_mode_16_64 3
		.amdhsa_dx10_clamp 1
		.amdhsa_ieee_mode 1
		.amdhsa_fp16_overflow 0
		.amdhsa_tg_split 0
		.amdhsa_exception_fp_ieee_invalid_op 0
		.amdhsa_exception_fp_denorm_src 0
		.amdhsa_exception_fp_ieee_div_zero 0
		.amdhsa_exception_fp_ieee_overflow 0
		.amdhsa_exception_fp_ieee_underflow 0
		.amdhsa_exception_fp_ieee_inexact 0
		.amdhsa_exception_int_div_zero 0
	.end_amdhsa_kernel

amdhsa.kernels:
  - .agpr_count:     0
    .args:
      - .offset:         0
        .size:           328
        .value_kind:     by_value
      - .offset:         328
        .size:           4
        .value_kind:     hidden_block_count_x
      - .offset:         332
        .size:           4
        .value_kind:     hidden_block_count_y
      - .offset:         336
        .size:           4
        .value_kind:     hidden_block_count_z
      - .offset:         340
        .size:           2
        .value_kind:     hidden_group_size_x
      - .offset:         342
        .size:           2
        .value_kind:     hidden_group_size_y
      - .offset:         344
        .size:           2
        .value_kind:     hidden_group_size_z
      - .offset:         346
        .size:           2
        .value_kind:     hidden_remainder_x
      - .offset:         348
        .size:           2
        .value_kind:     hidden_remainder_y
      - .offset:         350
        .size:           2
        .value_kind:     hidden_remainder_z
      - .offset:         368
        .size:           8
        .value_kind:     hidden_global_offset_x
      - .offset:         376
        .size:           8
        .value_kind:     hidden_global_offset_y
      - .offset:         384
        .size:           8
        .value_kind:     hidden_global_offset_z
      - .offset:         392
        .size:           2
        .value_kind:     hidden_grid_dims
      - .offset:         448
        .size:           4
        .value_kind:     hidden_dynamic_lds_size
    .group_segment_fixed_size: 0
    .kernarg_segment_align: 8
    .kernarg_segment_size: 584
    .language:       OpenCL C
    .language_version:
      - 2
      - 0
    .max_flat_workgroup_size: 512
    .name:           _Z10fwd_kernel4Args
    .private_segment_fixed_size: 0
    .sgpr_count:     108
    .sgpr_spill_count: 88
    .symbol:         _Z10fwd_kernel4Args.kd
    .uniform_work_group_size: 1
    .uses_dynamic_stack: false
    .vgpr_count:     256
    .vgpr_spill_count: 0
    .wavefront_size: 64
